# v55 plus gate_up epilogue: adjacent scalar x*-log2e and 1+e pairs packed into v_pk_mul_f32 / v_pk_add_f32 (same f32 results)
# baseline (speedup 1.0000x reference)
; __device__ __forceinline__ u32x4 pack8(f32x4 a, f32x4 b) { u32x4 w; w.x = cvt_pk_bf16(a[0], a[1]); w.y = cvt_pk_bf16(a[2], a[3]); w.z = cvt_pk_bf16(b[0], b[1]); w.w = cvt_pk_bf16(b[2], b[3]); return w; }
; __device__ __forceinline__ float silu_f(float v) { return v * __builtin_amdgcn_rcpf(1.0f + __builtin_amdgcn_exp2f(v * -1.4426950408889634f)); }
; __device__ __forceinline__ f32x4 silu4(f32x4 v) { return (f32x4){silu_f(v[0]), silu_f(v[1]), silu_f(v[2]), silu_f(v[3])}; }
;     __device__ __forceinline__ void operator()(const f32x4 (&acc)[2][2][4][2], const Unit& u, int wr, int wc, int fr, int fq) const {
;     ...
;         for (int ai = 0; ai < 2; ++ai)
; #pragma unroll
;             for (int m = 0; m < 4; ++m) {
;                 const int row = u.pm * BM + ai * HALF + wr * 64 + m * 16 + fr;
;                 const float rstd = rs[ai][m];
;                 const f32x4 a0 = silu4(acc[ai][0][m][0] * rstd) * (acc[ai][1][m][0] * rstd);
;                 const f32x4 a1 = silu4(acc[ai][0][m][1] * rstd) * (acc[ai][1][m][1] * rstd);
;                 *(u32x4*)(ACT + (size_t)row * 2816 + col0) = pack8(a0, a1);
;             }
.Lrsj_0:
	s_mov_b32 s98, 0xbfb8aa3b
	s_mov_b32 s99, 0xbfb8aa3b
	v_mov_b32_e32 v212, 1.0
	v_mov_b32_e32 v213, 1.0
	v_mul_f32_e32 v147, 0xbfb8aa3b, v124
	v_exp_f32_e32 v147, v147
	v_mul_f32_e32 v149, 0xbfb8aa3b, v125
	v_exp_f32_e32 v149, v149
	v_pk_mul_f32 v[126:127], v[126:127], v[176:177] op_sel_hi:[1,0]
	v_add_f32_e32 v147, 1.0, v147
	v_rcp_f32_e32 v178, v147
	v_add_f32_e32 v147, 1.0, v149
	v_mul_f32_e32 v149, 0xbfb8aa3b, v126
	v_exp_f32_e32 v149, v149
	v_mul_f32_e32 v151, 0xbfb8aa3b, v127
	v_exp_f32_e32 v151, v151
	v_rcp_f32_e32 v179, v147
	v_add_f32_e32 v147, 1.0, v149
	v_rcp_f32_e32 v180, v147
	v_add_f32_e32 v147, 1.0, v151
	v_pk_mul_f32 v[120:121], v[120:121], v[176:177] op_sel_hi:[1,0]
	v_rcp_f32_e32 v181, v147
	v_mul_f32_e32 v147, 0xbfb8aa3b, v120
	v_exp_f32_e32 v147, v147
	v_mul_f32_e32 v149, 0xbfb8aa3b, v121
	v_exp_f32_e32 v149, v149
	v_pk_mul_f32 v[122:123], v[122:123], v[176:177] op_sel_hi:[1,0]
	v_add_f32_e32 v147, 1.0, v147
	v_pk_mul_f32 v[124:125], v[124:125], v[178:179]
	v_rcp_f32_e32 v178, v147
	v_add_f32_e32 v147, 1.0, v149
	v_mul_f32_e32 v149, 0xbfb8aa3b, v122
	v_exp_f32_e32 v149, v149
	v_mul_f32_e32 v151, 0xbfb8aa3b, v123
	v_exp_f32_e32 v151, v151
	v_rcp_f32_e32 v179, v147
	v_add_f32_e32 v147, 1.0, v149
	v_pk_mul_f32 v[126:127], v[126:127], v[180:181]
	v_rcp_f32_e32 v180, v147
	v_add_f32_e32 v147, 1.0, v151
	v_rcp_f32_e32 v181, v147
	v_pk_mul_f32 v[116:117], v[116:117], v[176:177] op_sel_hi:[1,0]
	v_pk_mul_f32 v[118:119], v[118:119], v[176:177] op_sel_hi:[1,0]
	v_pk_mul_f32 v[120:121], v[120:121], v[178:179]
	v_pk_mul_f32 v[112:113], v[112:113], v[176:177] op_sel_hi:[1,0]
	v_lshl_or_b32 v182, s57, 7, v161
	v_pk_mul_f32 v[118:119], v[118:119], v[126:127]
	v_pk_mul_f32 v[116:117], v[116:117], v[124:125]
	v_pk_mul_f32 v[122:123], v[122:123], v[180:181]
	v_pk_mul_f32 v[114:115], v[114:115], v[176:177] op_sel_hi:[1,0]
	v_pk_mul_f32 v[112:113], v[112:113], v[120:121]
	v_ashrrev_i32_e32 v183, 31, v182
	v_pk_mul_f32 v[114:115], v[114:115], v[122:123]
	v_cvt_pk_bf16_f32 v116, v116, v117
	v_cvt_pk_bf16_f32 v117, v118, v119
	v_cvt_pk_bf16_f32 v118, v112, v113
	v_mov_b64_e32 v[112:113], s[14:15]
	v_cvt_pk_bf16_f32 v119, v114, v115
	v_mad_i64_i32 v[120:121], s[38:39], v170, s56, v[112:113]
	v_lshlrev_b64 v[114:115], 1, v[182:183]
	v_pk_mul_f32 v[108:109], v[108:109], v[174:175] op_sel_hi:[1,0]
	v_pk_mul_f32 v[110:111], v[110:111], v[174:175] op_sel_hi:[1,0]
	v_pk_mul_f32 v[122:123], v[108:109], s[98:99]
	v_lshl_add_u64 v[120:121], v[120:121], 0, v[114:115]
	v_pk_mul_f32 v[104:105], v[104:105], v[174:175] op_sel_hi:[1,0]
	v_pk_mul_f32 v[106:107], v[106:107], v[174:175] op_sel_hi:[1,0]
	v_exp_f32_e32 v122, v122
	v_exp_f32_e32 v123, v123
	v_pk_mul_f32 v[124:125], v[110:111], s[98:99]
	global_store_dwordx4 v[120:121], v[116:119], off
	v_exp_f32_e32 v124, v124
	v_exp_f32_e32 v125, v125
	v_pk_mul_f32 v[116:117], v[104:105], s[98:99]
	v_pk_mul_f32 v[118:119], v[106:107], s[98:99]
	v_exp_f32_e32 v116, v116
	v_exp_f32_e32 v117, v117
	v_exp_f32_e32 v118, v118
	v_exp_f32_e32 v119, v119
	v_pk_add_f32 v[122:123], v[122:123], v[212:213]
	v_rcp_f32_e32 v122, v122
	v_rcp_f32_e32 v123, v123
	v_pk_add_f32 v[124:125], v[124:125], v[212:213]
	v_pk_add_f32 v[116:117], v[116:117], v[212:213]
	v_pk_add_f32 v[118:119], v[118:119], v[212:213]
	v_rcp_f32_e32 v124, v124
	v_rcp_f32_e32 v125, v125
	v_rcp_f32_e32 v116, v116
	v_rcp_f32_e32 v117, v117
	v_rcp_f32_e32 v118, v118
	v_rcp_f32_e32 v119, v119
	v_pk_mul_f32 v[108:109], v[108:109], v[122:123]
	v_pk_mul_f32 v[100:101], v[100:101], v[174:175] op_sel_hi:[1,0]
	v_pk_mul_f32 v[110:111], v[110:111], v[124:125]
	v_pk_mul_f32 v[102:103], v[102:103], v[174:175] op_sel_hi:[1,0]
	v_pk_mul_f32 v[100:101], v[100:101], v[108:109]
	v_pk_mul_f32 v[104:105], v[104:105], v[116:117]
	v_pk_mul_f32 v[106:107], v[106:107], v[118:119]
	v_pk_mul_f32 v[96:97], v[96:97], v[174:175] op_sel_hi:[1,0]
	v_pk_mul_f32 v[98:99], v[98:99], v[174:175] op_sel_hi:[1,0]
	v_pk_mul_f32 v[102:103], v[102:103], v[110:111]
	v_pk_mul_f32 v[106:107], v[98:99], v[106:107]
	v_pk_mul_f32 v[98:99], v[96:97], v[104:105]
	v_cvt_pk_bf16_f32 v96, v100, v101
	v_mad_i64_i32 v[100:101], s[38:39], v166, s56, v[112:113]
	v_pk_mul_f32 v[92:93], v[92:93], v[172:173] op_sel_hi:[1,0]
	v_cvt_pk_bf16_f32 v97, v102, v103
	v_cvt_pk_bf16_f32 v98, v98, v99
	v_cvt_pk_bf16_f32 v99, v106, v107
	v_pk_mul_f32 v[94:95], v[94:95], v[172:173] op_sel_hi:[1,0]
	v_pk_mul_f32 v[102:103], v[92:93], s[98:99]
	v_lshl_add_u64 v[100:101], v[100:101], 0, v[114:115]
	v_pk_mul_f32 v[88:89], v[88:89], v[172:173] op_sel_hi:[1,0]
	v_pk_mul_f32 v[90:91], v[90:91], v[172:173] op_sel_hi:[1,0]
	v_exp_f32_e32 v102, v102
	v_exp_f32_e32 v103, v103
	v_pk_mul_f32 v[104:105], v[94:95], s[98:99]
	global_store_dwordx4 v[100:101], v[96:99], off
	v_exp_f32_e32 v104, v104
	v_exp_f32_e32 v105, v105
	v_pk_mul_f32 v[96:97], v[88:89], s[98:99]
	v_pk_mul_f32 v[98:99], v[90:91], s[98:99]
	v_exp_f32_e32 v96, v96
	v_exp_f32_e32 v97, v97
	v_exp_f32_e32 v98, v98
	v_exp_f32_e32 v99, v99
	v_pk_add_f32 v[102:103], v[102:103], v[212:213]
	v_rcp_f32_e32 v102, v102
	v_rcp_f32_e32 v103, v103
	v_pk_add_f32 v[104:105], v[104:105], v[212:213]
	v_pk_add_f32 v[96:97], v[96:97], v[212:213]
	v_pk_add_f32 v[98:99], v[98:99], v[212:213]
	v_rcp_f32_e32 v104, v104
	v_rcp_f32_e32 v105, v105
	v_rcp_f32_e32 v96, v96
	v_rcp_f32_e32 v97, v97
	v_rcp_f32_e32 v98, v98
	v_rcp_f32_e32 v99, v99
	v_pk_mul_f32 v[92:93], v[92:93], v[102:103]
	v_pk_mul_f32 v[84:85], v[84:85], v[172:173] op_sel_hi:[1,0]
	v_pk_mul_f32 v[94:95], v[94:95], v[104:105]
	v_pk_mul_f32 v[86:87], v[86:87], v[172:173] op_sel_hi:[1,0]
	v_pk_mul_f32 v[84:85], v[84:85], v[92:93]
; __device__ __forceinline__ u32x4 pack8(f32x4 a, f32x4 b) { u32x4 w; w.x = cvt_pk_bf16(a[0], a[1]); w.y = cvt_pk_bf16(a[2], a[3]); w.z = cvt_pk_bf16(b[0], b[1]); w.w = cvt_pk_bf16(b[2], b[3]); return w; }
; __device__ __forceinline__ float silu_f(float v) { return v * __builtin_amdgcn_rcpf(1.0f + __builtin_amdgcn_exp2f(v * -1.4426950408889634f)); }
; __device__ __forceinline__ f32x4 silu4(f32x4 v) { return (f32x4){silu_f(v[0]), silu_f(v[1]), silu_f(v[2]), silu_f(v[3])}; }
;     __device__ __forceinline__ void operator()(const f32x4 (&acc)[2][2][4][2], const Unit& u, int wr, int wc, int fr, int fq) const {
;     ...
;         for (int ai = 0; ai < 2; ++ai)
; #pragma unroll
;             for (int m = 0; m < 4; ++m) {
;                 const int row = u.pm * BM + ai * HALF + wr * 64 + m * 16 + fr;
;                 const float rstd = rs[ai][m];
;                 const f32x4 a0 = silu4(acc[ai][0][m][0] * rstd) * (acc[ai][1][m][0] * rstd);
;                 const f32x4 a1 = silu4(acc[ai][0][m][1] * rstd) * (acc[ai][1][m][1] * rstd);
;                 *(u32x4*)(ACT + (size_t)row * 2816 + col0) = pack8(a0, a1);
;             }
	v_pk_mul_f32 v[88:89], v[88:89], v[96:97]
	v_pk_mul_f32 v[90:91], v[90:91], v[98:99]
	v_pk_mul_f32 v[80:81], v[80:81], v[172:173] op_sel_hi:[1,0]
	v_pk_mul_f32 v[82:83], v[82:83], v[172:173] op_sel_hi:[1,0]
	v_pk_mul_f32 v[86:87], v[86:87], v[94:95]
	v_pk_mul_f32 v[90:91], v[82:83], v[90:91]
	v_pk_mul_f32 v[82:83], v[80:81], v[88:89]
	v_cvt_pk_bf16_f32 v80, v84, v85
	v_mad_i64_i32 v[84:85], s[38:39], v162, s56, v[112:113]
	v_pk_mul_f32 v[76:77], v[76:77], v[168:169] op_sel_hi:[1,0]
	v_cvt_pk_bf16_f32 v81, v86, v87
	v_cvt_pk_bf16_f32 v82, v82, v83
	v_cvt_pk_bf16_f32 v83, v90, v91
	v_pk_mul_f32 v[78:79], v[78:79], v[168:169] op_sel_hi:[1,0]
	v_pk_mul_f32 v[86:87], v[76:77], s[98:99]
	v_lshl_add_u64 v[84:85], v[84:85], 0, v[114:115]
	v_pk_mul_f32 v[72:73], v[72:73], v[168:169] op_sel_hi:[1,0]
	v_pk_mul_f32 v[74:75], v[74:75], v[168:169] op_sel_hi:[1,0]
	v_exp_f32_e32 v86, v86
	v_exp_f32_e32 v87, v87
	v_pk_mul_f32 v[88:89], v[78:79], s[98:99]
	global_store_dwordx4 v[84:85], v[80:83], off
	v_exp_f32_e32 v88, v88
	v_exp_f32_e32 v89, v89
	v_pk_mul_f32 v[80:81], v[72:73], s[98:99]
	v_pk_mul_f32 v[82:83], v[74:75], s[98:99]
	v_exp_f32_e32 v80, v80
	v_exp_f32_e32 v81, v81
	v_exp_f32_e32 v82, v82
	v_exp_f32_e32 v83, v83
	v_pk_add_f32 v[86:87], v[86:87], v[212:213]
	v_rcp_f32_e32 v86, v86
	v_rcp_f32_e32 v87, v87
	v_pk_add_f32 v[88:89], v[88:89], v[212:213]
	v_pk_add_f32 v[80:81], v[80:81], v[212:213]
	v_pk_add_f32 v[82:83], v[82:83], v[212:213]
	v_rcp_f32_e32 v88, v88
	v_rcp_f32_e32 v89, v89
	v_rcp_f32_e32 v80, v80
	v_rcp_f32_e32 v81, v81
	v_rcp_f32_e32 v82, v82
	v_rcp_f32_e32 v83, v83
	v_pk_mul_f32 v[76:77], v[76:77], v[86:87]
	v_pk_mul_f32 v[68:69], v[68:69], v[168:169] op_sel_hi:[1,0]
	v_pk_mul_f32 v[78:79], v[78:79], v[88:89]
	v_pk_mul_f32 v[70:71], v[70:71], v[168:169] op_sel_hi:[1,0]
	v_pk_mul_f32 v[68:69], v[68:69], v[76:77]
	v_pk_mul_f32 v[72:73], v[72:73], v[80:81]
	v_pk_mul_f32 v[74:75], v[74:75], v[82:83]
	v_pk_mul_f32 v[64:65], v[64:65], v[168:169] op_sel_hi:[1,0]
	v_pk_mul_f32 v[66:67], v[66:67], v[168:169] op_sel_hi:[1,0]
	v_pk_mul_f32 v[70:71], v[70:71], v[78:79]
	v_pk_mul_f32 v[74:75], v[66:67], v[74:75]
	v_pk_mul_f32 v[66:67], v[64:65], v[72:73]
	v_cvt_pk_bf16_f32 v64, v68, v69
	v_mad_i64_i32 v[68:69], s[38:39], v158, s56, v[112:113]
	v_pk_mul_f32 v[60:61], v[60:61], v[164:165] op_sel_hi:[1,0]
	v_cvt_pk_bf16_f32 v65, v70, v71
	v_cvt_pk_bf16_f32 v66, v66, v67
	v_cvt_pk_bf16_f32 v67, v74, v75
	v_pk_mul_f32 v[62:63], v[62:63], v[164:165] op_sel_hi:[1,0]
	v_pk_mul_f32 v[70:71], v[60:61], s[98:99]
	v_lshl_add_u64 v[68:69], v[68:69], 0, v[114:115]
	v_pk_mul_f32 v[56:57], v[56:57], v[164:165] op_sel_hi:[1,0]
	v_pk_mul_f32 v[58:59], v[58:59], v[164:165] op_sel_hi:[1,0]
	v_exp_f32_e32 v70, v70
	v_exp_f32_e32 v71, v71
	v_pk_mul_f32 v[72:73], v[62:63], s[98:99]
	global_store_dwordx4 v[68:69], v[64:67], off
	v_exp_f32_e32 v72, v72
	v_exp_f32_e32 v73, v73
	v_pk_mul_f32 v[64:65], v[56:57], s[98:99]
	v_pk_mul_f32 v[66:67], v[58:59], s[98:99]
	v_exp_f32_e32 v64, v64
	v_exp_f32_e32 v65, v65
	v_exp_f32_e32 v66, v66
	v_exp_f32_e32 v67, v67
	v_pk_add_f32 v[70:71], v[70:71], v[212:213]
	v_rcp_f32_e32 v70, v70
	v_rcp_f32_e32 v71, v71
	v_pk_add_f32 v[72:73], v[72:73], v[212:213]
	v_pk_add_f32 v[64:65], v[64:65], v[212:213]
	v_pk_add_f32 v[66:67], v[66:67], v[212:213]
	v_rcp_f32_e32 v72, v72
	v_rcp_f32_e32 v73, v73
	v_rcp_f32_e32 v64, v64
	v_rcp_f32_e32 v65, v65
	v_rcp_f32_e32 v66, v66
	v_rcp_f32_e32 v67, v67
	v_pk_mul_f32 v[60:61], v[60:61], v[70:71]
	v_pk_mul_f32 v[52:53], v[52:53], v[164:165] op_sel_hi:[1,0]
	v_pk_mul_f32 v[62:63], v[62:63], v[72:73]
	v_pk_mul_f32 v[54:55], v[54:55], v[164:165] op_sel_hi:[1,0]
	v_pk_mul_f32 v[52:53], v[52:53], v[60:61]
	v_pk_mul_f32 v[56:57], v[56:57], v[64:65]
	v_pk_mul_f32 v[58:59], v[58:59], v[66:67]
	v_pk_mul_f32 v[48:49], v[48:49], v[164:165] op_sel_hi:[1,0]
	v_pk_mul_f32 v[50:51], v[50:51], v[164:165] op_sel_hi:[1,0]
	v_pk_mul_f32 v[54:55], v[54:55], v[62:63]
	v_pk_mul_f32 v[58:59], v[50:51], v[58:59]
	v_pk_mul_f32 v[50:51], v[48:49], v[56:57]
	v_cvt_pk_bf16_f32 v48, v52, v53
	v_mad_i64_i32 v[52:53], s[38:39], v154, s56, v[112:113]
	v_pk_mul_f32 v[44:45], v[44:45], v[160:161] op_sel_hi:[1,0]
	v_cvt_pk_bf16_f32 v49, v54, v55
	v_cvt_pk_bf16_f32 v50, v50, v51
	v_cvt_pk_bf16_f32 v51, v58, v59
	v_pk_mul_f32 v[46:47], v[46:47], v[160:161] op_sel_hi:[1,0]
	v_pk_mul_f32 v[54:55], v[44:45], s[98:99]
	v_lshl_add_u64 v[52:53], v[52:53], 0, v[114:115]
	v_pk_mul_f32 v[40:41], v[40:41], v[160:161] op_sel_hi:[1,0]
	v_pk_mul_f32 v[42:43], v[42:43], v[160:161] op_sel_hi:[1,0]
	v_exp_f32_e32 v54, v54
	v_exp_f32_e32 v55, v55
	v_pk_mul_f32 v[56:57], v[46:47], s[98:99]
	global_store_dwordx4 v[52:53], v[48:51], off
	v_exp_f32_e32 v56, v56
	v_exp_f32_e32 v57, v57
	v_pk_mul_f32 v[48:49], v[40:41], s[98:99]
	v_pk_mul_f32 v[50:51], v[42:43], s[98:99]
	v_exp_f32_e32 v48, v48
	v_exp_f32_e32 v49, v49
	v_exp_f32_e32 v50, v50
	v_exp_f32_e32 v51, v51
	v_pk_add_f32 v[54:55], v[54:55], v[212:213]
; __device__ __forceinline__ u32x4 pack8(f32x4 a, f32x4 b) { u32x4 w; w.x = cvt_pk_bf16(a[0], a[1]); w.y = cvt_pk_bf16(a[2], a[3]); w.z = cvt_pk_bf16(b[0], b[1]); w.w = cvt_pk_bf16(b[2], b[3]); return w; }
; __device__ __forceinline__ float silu_f(float v) { return v * __builtin_amdgcn_rcpf(1.0f + __builtin_amdgcn_exp2f(v * -1.4426950408889634f)); }
; __device__ __forceinline__ f32x4 silu4(f32x4 v) { return (f32x4){silu_f(v[0]), silu_f(v[1]), silu_f(v[2]), silu_f(v[3])}; }
;     __device__ __forceinline__ void operator()(const f32x4 (&acc)[2][2][4][2], const Unit& u, int wr, int wc, int fr, int fq) const {
;     ...
;         for (int ai = 0; ai < 2; ++ai)
; #pragma unroll
;             for (int m = 0; m < 4; ++m) {
;                 const int row = u.pm * BM + ai * HALF + wr * 64 + m * 16 + fr;
;                 const float rstd = rs[ai][m];
;                 const f32x4 a0 = silu4(acc[ai][0][m][0] * rstd) * (acc[ai][1][m][0] * rstd);
;                 const f32x4 a1 = silu4(acc[ai][0][m][1] * rstd) * (acc[ai][1][m][1] * rstd);
;                 *(u32x4*)(ACT + (size_t)row * 2816 + col0) = pack8(a0, a1);
;             }
	v_rcp_f32_e32 v54, v54
	v_rcp_f32_e32 v55, v55
	v_pk_add_f32 v[56:57], v[56:57], v[212:213]
	v_pk_add_f32 v[48:49], v[48:49], v[212:213]
	v_pk_add_f32 v[50:51], v[50:51], v[212:213]
	v_rcp_f32_e32 v56, v56
	v_rcp_f32_e32 v57, v57
	v_rcp_f32_e32 v48, v48
	v_rcp_f32_e32 v49, v49
	v_rcp_f32_e32 v50, v50
	v_rcp_f32_e32 v51, v51
	v_pk_mul_f32 v[44:45], v[44:45], v[54:55]
	v_pk_mul_f32 v[36:37], v[36:37], v[160:161] op_sel_hi:[1,0]
	v_pk_mul_f32 v[46:47], v[46:47], v[56:57]
	v_pk_mul_f32 v[38:39], v[38:39], v[160:161] op_sel_hi:[1,0]
	v_pk_mul_f32 v[36:37], v[36:37], v[44:45]
	v_pk_mul_f32 v[40:41], v[40:41], v[48:49]
	v_pk_mul_f32 v[42:43], v[42:43], v[50:51]
	v_pk_mul_f32 v[32:33], v[32:33], v[160:161] op_sel_hi:[1,0]
	v_pk_mul_f32 v[34:35], v[34:35], v[160:161] op_sel_hi:[1,0]
	v_pk_mul_f32 v[38:39], v[38:39], v[46:47]
	v_pk_mul_f32 v[42:43], v[34:35], v[42:43]
	v_pk_mul_f32 v[34:35], v[32:33], v[40:41]
	v_cvt_pk_bf16_f32 v32, v36, v37
	v_mad_i64_i32 v[36:37], s[38:39], v150, s56, v[112:113]
	v_pk_mul_f32 v[28:29], v[28:29], v[156:157] op_sel_hi:[1,0]
	v_cvt_pk_bf16_f32 v33, v38, v39
	v_cvt_pk_bf16_f32 v34, v34, v35
	v_cvt_pk_bf16_f32 v35, v42, v43
	v_pk_mul_f32 v[30:31], v[30:31], v[156:157] op_sel_hi:[1,0]
	v_pk_mul_f32 v[38:39], v[28:29], s[98:99]
	v_lshl_add_u64 v[36:37], v[36:37], 0, v[114:115]
	v_pk_mul_f32 v[24:25], v[24:25], v[156:157] op_sel_hi:[1,0]
	v_pk_mul_f32 v[26:27], v[26:27], v[156:157] op_sel_hi:[1,0]
	v_exp_f32_e32 v38, v38
	v_exp_f32_e32 v39, v39
	v_pk_mul_f32 v[40:41], v[30:31], s[98:99]
	global_store_dwordx4 v[36:37], v[32:35], off
	v_exp_f32_e32 v40, v40
	v_exp_f32_e32 v41, v41
	v_pk_mul_f32 v[32:33], v[24:25], s[98:99]
	v_pk_mul_f32 v[34:35], v[26:27], s[98:99]
	v_exp_f32_e32 v32, v32
	v_exp_f32_e32 v33, v33
	v_exp_f32_e32 v34, v34
	v_exp_f32_e32 v35, v35
	v_pk_add_f32 v[38:39], v[38:39], v[212:213]
	v_rcp_f32_e32 v38, v38
	v_rcp_f32_e32 v39, v39
	v_pk_add_f32 v[40:41], v[40:41], v[212:213]
	v_pk_add_f32 v[32:33], v[32:33], v[212:213]
	v_pk_add_f32 v[34:35], v[34:35], v[212:213]
	v_rcp_f32_e32 v40, v40
	v_rcp_f32_e32 v41, v41
	v_rcp_f32_e32 v32, v32
	v_rcp_f32_e32 v33, v33
	v_rcp_f32_e32 v34, v34
	v_rcp_f32_e32 v35, v35
	v_pk_mul_f32 v[28:29], v[28:29], v[38:39]
	v_pk_mul_f32 v[20:21], v[20:21], v[156:157] op_sel_hi:[1,0]
	v_pk_mul_f32 v[30:31], v[30:31], v[40:41]
	v_pk_mul_f32 v[22:23], v[22:23], v[156:157] op_sel_hi:[1,0]
	v_pk_mul_f32 v[20:21], v[20:21], v[28:29]
	v_pk_mul_f32 v[24:25], v[24:25], v[32:33]
	v_pk_mul_f32 v[26:27], v[26:27], v[34:35]
	v_pk_mul_f32 v[16:17], v[16:17], v[156:157] op_sel_hi:[1,0]
	v_pk_mul_f32 v[18:19], v[18:19], v[156:157] op_sel_hi:[1,0]
	v_pk_mul_f32 v[22:23], v[22:23], v[30:31]
	v_pk_mul_f32 v[26:27], v[18:19], v[26:27]
	v_pk_mul_f32 v[18:19], v[16:17], v[24:25]
	v_cvt_pk_bf16_f32 v16, v20, v21
	v_mad_i64_i32 v[20:21], s[38:39], v148, s56, v[112:113]
	v_pk_mul_f32 v[12:13], v[12:13], v[152:153] op_sel_hi:[1,0]
	v_cvt_pk_bf16_f32 v17, v22, v23
	v_cvt_pk_bf16_f32 v18, v18, v19
	v_cvt_pk_bf16_f32 v19, v26, v27
	v_lshl_add_u64 v[20:21], v[20:21], 0, v[114:115]
	v_pk_mul_f32 v[22:23], v[12:13], s[98:99]
	v_pk_mul_f32 v[8:9], v[8:9], v[152:153] op_sel_hi:[1,0]
	v_pk_mul_f32 v[10:11], v[10:11], v[152:153] op_sel_hi:[1,0]
	v_exp_f32_e32 v22, v22
	v_exp_f32_e32 v23, v23
	global_store_dwordx4 v[20:21], v[16:19], off
	v_pk_mul_f32 v[14:15], v[14:15], v[152:153] op_sel_hi:[1,0]
	v_add_f32_e32 v22, 1.0, v22
	v_pk_mul_f32 v[16:17], v[8:9], s[98:99]
	v_pk_mul_f32 v[18:19], v[10:11], s[98:99]
	v_exp_f32_e32 v16, v16
	v_exp_f32_e32 v17, v17
	v_exp_f32_e32 v18, v18
	v_exp_f32_e32 v19, v19
	v_pk_mul_f32 v[24:25], v[14:15], s[98:99]
	v_exp_f32_e32 v24, v24
	v_exp_f32_e32 v25, v25
	v_add_f32_e32 v23, 1.0, v23
	v_rcp_f32_e32 v22, v22
	v_rcp_f32_e32 v23, v23
	v_pk_add_f32 v[16:17], v[16:17], v[212:213]
	v_pk_add_f32 v[18:19], v[18:19], v[212:213]
	v_rcp_f32_e32 v16, v16
	v_rcp_f32_e32 v17, v17
	v_rcp_f32_e32 v18, v18
	v_rcp_f32_e32 v19, v19
	v_pk_add_f32 v[24:25], v[24:25], v[212:213]
	v_rcp_f32_e32 v24, v24
	v_rcp_f32_e32 v25, v25
	v_pk_mul_f32 v[12:13], v[12:13], v[22:23]
	v_pk_mul_f32 v[4:5], v[4:5], v[152:153] op_sel_hi:[1,0]
	v_pk_mul_f32 v[8:9], v[8:9], v[16:17]
	v_pk_mul_f32 v[4:5], v[4:5], v[12:13]
	v_pk_mul_f32 v[10:11], v[10:11], v[18:19]
	v_pk_mul_f32 v[0:1], v[0:1], v[152:153] op_sel_hi:[1,0]
	v_pk_mul_f32 v[2:3], v[2:3], v[152:153] op_sel_hi:[1,0]
	v_pk_mul_f32 v[14:15], v[14:15], v[24:25]
	v_pk_mul_f32 v[10:11], v[2:3], v[10:11]
	v_pk_mul_f32 v[2:3], v[0:1], v[8:9]
	v_cvt_pk_bf16_f32 v0, v4, v5
	v_mad_i64_i32 v[4:5], s[38:39], v146, s56, v[112:113]
	v_pk_mul_f32 v[6:7], v[6:7], v[152:153] op_sel_hi:[1,0]
	v_lshl_add_u64 v[4:5], v[4:5], 0, v[114:115]
	v_pk_mul_f32 v[6:7], v[6:7], v[14:15]
	s_nop 0
	v_cvt_pk_bf16_f32 v1, v6, v7
	v_cvt_pk_bf16_f32 v2, v2, v3
	v_cvt_pk_bf16_f32 v3, v10, v11
	global_store_dwordx4 v[4:5], v[0:3], off
	s_cbranch_vccnz .LBB0_516
	s_andn2_b64 vcc, exec, s[12:13]
	s_cbranch_vccnz .LBB0_515
	s_barrier
	s_branch .LBB0_515

; __device__ __forceinline__ u32x4 pack8(f32x4 a, f32x4 b) { u32x4 w; w.x = cvt_pk_bf16(a[0], a[1]); w.y = cvt_pk_bf16(a[2], a[3]); w.z = cvt_pk_bf16(b[0], b[1]); w.w = cvt_pk_bf16(b[2], b[3]); return w; }
; __device__ __forceinline__ float silu_f(float v) { return v * __builtin_amdgcn_rcpf(1.0f + __builtin_amdgcn_exp2f(v * -1.4426950408889634f)); }
; __device__ __forceinline__ f32x4 silu4(f32x4 v) { return (f32x4){silu_f(v[0]), silu_f(v[1]), silu_f(v[2]), silu_f(v[3])}; }
;     __device__ __forceinline__ void operator()(const f32x4 (&acc)[2][2][4][2], const Unit& u, int wr, int wc, int fr, int fq) const {
;     ...
;         for (int ai = 0; ai < 2; ++ai)
; #pragma unroll
;             for (int m = 0; m < 4; ++m) {
;                 const int row = u.pm * BM + ai * HALF + wr * 64 + m * 16 + fr;
;                 const float rstd = rs[ai][m];
;                 const f32x4 a0 = silu4(acc[ai][0][m][0] * rstd) * (acc[ai][1][m][0] * rstd);
;                 const f32x4 a1 = silu4(acc[ai][0][m][1] * rstd) * (acc[ai][1][m][1] * rstd);
;                 *(u32x4*)(ACT + (size_t)row * 2816 + col0) = pack8(a0, a1);
;             }
.Lrsj_1:
	s_mov_b32 s98, 0xbfb8aa3b
	s_mov_b32 s99, 0xbfb8aa3b
	v_mov_b32_e32 v184, 1.0
	v_mov_b32_e32 v185, 1.0
	v_mul_f32_e32 v147, 0xbfb8aa3b, v124
	v_exp_f32_e32 v147, v147
	v_pk_mul_f32 v[14:15], v[14:15], v[154:155] op_sel_hi:[1,0]
	v_pk_mul_f32 v[12:13], v[12:13], v[154:155] op_sel_hi:[1,0]
	v_add_f32_e32 v147, 1.0, v147
	v_rcp_f32_e32 v180, v147
	v_mul_f32_e32 v147, 0xbfb8aa3b, v125
	v_exp_f32_e32 v147, v147
	v_pk_mul_f32 v[4:5], v[4:5], v[154:155] op_sel_hi:[1,0]
	v_pk_mul_f32 v[6:7], v[6:7], v[154:155] op_sel_hi:[1,0]
	v_pk_mul_f32 v[10:11], v[10:11], v[154:155] op_sel_hi:[1,0]
	v_add_f32_e32 v147, 1.0, v147
	v_rcp_f32_e32 v181, v147
	v_mul_f32_e32 v147, 0xbfb8aa3b, v126
	v_exp_f32_e32 v147, v147
	v_pk_mul_f32 v[8:9], v[8:9], v[154:155] op_sel_hi:[1,0]
	v_pk_mul_f32 v[124:125], v[124:125], v[180:181]
	v_pk_mul_f32 v[0:1], v[0:1], v[154:155] op_sel_hi:[1,0]
	v_add_f32_e32 v147, 1.0, v147
	v_rcp_f32_e32 v182, v147
	v_mul_f32_e32 v147, 0xbfb8aa3b, v127
	v_exp_f32_e32 v147, v147
	v_pk_mul_f32 v[116:117], v[116:117], v[124:125]
	v_pk_mul_f32 v[124:125], v[120:121], s[98:99]
	v_add_f32_e32 v147, 1.0, v147
	v_rcp_f32_e32 v183, v147
	v_exp_f32_e32 v124, v124
	v_exp_f32_e32 v125, v125
	v_cvt_pk_bf16_f32 v116, v116, v117
	v_pk_mul_f32 v[126:127], v[126:127], v[182:183]
	v_add_f32_e32 v124, 1.0, v124
	v_pk_mul_f32 v[118:119], v[118:119], v[126:127]
	v_pk_mul_f32 v[126:127], v[122:123], s[98:99]
	v_exp_f32_e32 v126, v126
	v_exp_f32_e32 v127, v127
	v_add_f32_e32 v125, 1.0, v125
	v_rcp_f32_e32 v124, v124
	v_rcp_f32_e32 v125, v125
	v_pk_add_f32 v[126:127], v[126:127], v[184:185]
	v_rcp_f32_e32 v126, v126
	v_rcp_f32_e32 v127, v127
	v_pk_mul_f32 v[120:121], v[120:121], v[124:125]
	v_cvt_pk_bf16_f32 v117, v118, v119
	v_pk_mul_f32 v[2:3], v[2:3], v[154:155] op_sel_hi:[1,0]
	v_pk_mul_f32 v[122:123], v[122:123], v[126:127]
	v_pk_mul_f32 v[112:113], v[112:113], v[120:121]
	v_pk_mul_f32 v[114:115], v[114:115], v[122:123]
	v_cvt_pk_bf16_f32 v118, v112, v113
	v_mov_b64_e32 v[112:113], s[20:21]
	v_cvt_pk_bf16_f32 v119, v114, v115
	v_mad_i64_i32 v[120:121], s[14:15], v168, s68, v[112:113]
	v_lshlrev_b64 v[114:115], 1, v[178:179]
	v_lshl_add_u64 v[120:121], v[120:121], 0, v[114:115]
	global_store_dwordx4 v[120:121], v[116:119], off
	s_nop 1
	v_pk_mul_f32 v[116:117], v[108:109], s[98:99]
	v_pk_mul_f32 v[118:119], v[110:111], s[98:99]
	v_exp_f32_e32 v116, v116
	v_exp_f32_e32 v117, v117
	v_exp_f32_e32 v118, v118
	v_exp_f32_e32 v119, v119
	v_pk_add_f32 v[116:117], v[116:117], v[184:185]
	v_pk_add_f32 v[118:119], v[118:119], v[184:185]
	v_rcp_f32_e32 v116, v116
	v_rcp_f32_e32 v117, v117
	v_rcp_f32_e32 v118, v118
	v_rcp_f32_e32 v119, v119
	v_pk_mul_f32 v[108:109], v[108:109], v[116:117]
	s_nop 0
	v_pk_mul_f32 v[100:101], v[100:101], v[108:109]
	v_pk_mul_f32 v[110:111], v[110:111], v[118:119]
	v_mul_f32_e32 v108, 0xbfb8aa3b, v104
	v_pk_mul_f32 v[102:103], v[102:103], v[110:111]
	v_mul_f32_e32 v109, 0xbfb8aa3b, v105
	v_pk_mul_f32 v[110:111], v[106:107], s[98:99]
	v_exp_f32_e32 v108, v108
	v_exp_f32_e32 v109, v109
	v_exp_f32_e32 v110, v110
	v_exp_f32_e32 v111, v111
	v_pk_add_f32 v[108:109], v[108:109], v[184:185]
	v_pk_add_f32 v[110:111], v[110:111], v[184:185]
	v_rcp_f32_e32 v108, v108
	v_rcp_f32_e32 v109, v109
	v_rcp_f32_e32 v110, v110
	v_rcp_f32_e32 v111, v111
	v_pk_mul_f32 v[104:105], v[104:105], v[108:109]
	v_pk_mul_f32 v[106:107], v[106:107], v[110:111]
	s_nop 0
	v_pk_mul_f32 v[106:107], v[98:99], v[106:107]
	v_pk_mul_f32 v[98:99], v[96:97], v[104:105]
	v_cvt_pk_bf16_f32 v96, v100, v101
	v_mad_i64_i32 v[100:101], s[14:15], v164, s68, v[112:113]
	v_cvt_pk_bf16_f32 v97, v102, v103
	v_cvt_pk_bf16_f32 v98, v98, v99
	v_cvt_pk_bf16_f32 v99, v106, v107
	v_lshl_add_u64 v[100:101], v[100:101], 0, v[114:115]
	global_store_dwordx4 v[100:101], v[96:99], off
	s_nop 1
	v_pk_mul_f32 v[96:97], v[92:93], s[98:99]
	v_pk_mul_f32 v[98:99], v[94:95], s[98:99]
	v_exp_f32_e32 v96, v96
	v_exp_f32_e32 v97, v97
	v_exp_f32_e32 v98, v98
	v_exp_f32_e32 v99, v99
	v_pk_add_f32 v[96:97], v[96:97], v[184:185]
	v_pk_add_f32 v[98:99], v[98:99], v[184:185]
	v_rcp_f32_e32 v96, v96
	v_rcp_f32_e32 v97, v97
	v_rcp_f32_e32 v98, v98
	v_rcp_f32_e32 v99, v99
	v_pk_mul_f32 v[92:93], v[92:93], v[96:97]
	s_nop 0
	v_pk_mul_f32 v[84:85], v[84:85], v[92:93]
	v_pk_mul_f32 v[94:95], v[94:95], v[98:99]
	v_mul_f32_e32 v92, 0xbfb8aa3b, v88
	v_pk_mul_f32 v[86:87], v[86:87], v[94:95]
	v_mul_f32_e32 v93, 0xbfb8aa3b, v89
	v_pk_mul_f32 v[94:95], v[90:91], s[98:99]
	v_exp_f32_e32 v92, v92
	v_exp_f32_e32 v93, v93
	v_exp_f32_e32 v94, v94
	v_exp_f32_e32 v95, v95
	v_pk_add_f32 v[92:93], v[92:93], v[184:185]
	v_pk_add_f32 v[94:95], v[94:95], v[184:185]
	v_rcp_f32_e32 v92, v92
	v_rcp_f32_e32 v93, v93
	v_rcp_f32_e32 v94, v94
	v_rcp_f32_e32 v95, v95
	v_pk_mul_f32 v[88:89], v[88:89], v[92:93]
	v_pk_mul_f32 v[90:91], v[90:91], v[94:95]
	s_nop 0
	v_pk_mul_f32 v[90:91], v[82:83], v[90:91]
	v_pk_mul_f32 v[82:83], v[80:81], v[88:89]
	v_cvt_pk_bf16_f32 v80, v84, v85
	v_mad_i64_i32 v[84:85], s[14:15], v160, s68, v[112:113]
	v_cvt_pk_bf16_f32 v81, v86, v87
	v_cvt_pk_bf16_f32 v82, v82, v83
	v_cvt_pk_bf16_f32 v83, v90, v91
	v_lshl_add_u64 v[84:85], v[84:85], 0, v[114:115]
	global_store_dwordx4 v[84:85], v[80:83], off
	s_nop 1
	v_pk_mul_f32 v[80:81], v[76:77], s[98:99]
	v_pk_mul_f32 v[82:83], v[78:79], s[98:99]
	v_exp_f32_e32 v80, v80
	v_exp_f32_e32 v81, v81
	v_exp_f32_e32 v82, v82
	v_exp_f32_e32 v83, v83
	v_pk_add_f32 v[80:81], v[80:81], v[184:185]
	v_pk_add_f32 v[82:83], v[82:83], v[184:185]
	v_rcp_f32_e32 v80, v80
	v_rcp_f32_e32 v81, v81
	v_rcp_f32_e32 v82, v82
	v_rcp_f32_e32 v83, v83
	v_pk_mul_f32 v[76:77], v[76:77], v[80:81]
; __device__ __forceinline__ u32x4 pack8(f32x4 a, f32x4 b) { u32x4 w; w.x = cvt_pk_bf16(a[0], a[1]); w.y = cvt_pk_bf16(a[2], a[3]); w.z = cvt_pk_bf16(b[0], b[1]); w.w = cvt_pk_bf16(b[2], b[3]); return w; }
; __device__ __forceinline__ float silu_f(float v) { return v * __builtin_amdgcn_rcpf(1.0f + __builtin_amdgcn_exp2f(v * -1.4426950408889634f)); }
; __device__ __forceinline__ f32x4 silu4(f32x4 v) { return (f32x4){silu_f(v[0]), silu_f(v[1]), silu_f(v[2]), silu_f(v[3])}; }
;     __device__ __forceinline__ void operator()(const f32x4 (&acc)[2][2][4][2], const Unit& u, int wr, int wc, int fr, int fq) const {
;     ...
;         for (int ai = 0; ai < 2; ++ai)
; #pragma unroll
;             for (int m = 0; m < 4; ++m) {
;                 const int row = u.pm * BM + ai * HALF + wr * 64 + m * 16 + fr;
;                 const float rstd = rs[ai][m];
;                 const f32x4 a0 = silu4(acc[ai][0][m][0] * rstd) * (acc[ai][1][m][0] * rstd);
;                 const f32x4 a1 = silu4(acc[ai][0][m][1] * rstd) * (acc[ai][1][m][1] * rstd);
;                 *(u32x4*)(ACT + (size_t)row * 2816 + col0) = pack8(a0, a1);
;             }
	s_nop 0
	v_pk_mul_f32 v[68:69], v[68:69], v[76:77]
	v_pk_mul_f32 v[78:79], v[78:79], v[82:83]
	v_mul_f32_e32 v76, 0xbfb8aa3b, v72
	v_pk_mul_f32 v[70:71], v[70:71], v[78:79]
	v_mul_f32_e32 v77, 0xbfb8aa3b, v73
	v_pk_mul_f32 v[78:79], v[74:75], s[98:99]
	v_exp_f32_e32 v76, v76
	v_exp_f32_e32 v77, v77
	v_exp_f32_e32 v78, v78
	v_exp_f32_e32 v79, v79
	v_pk_add_f32 v[76:77], v[76:77], v[184:185]
	v_pk_add_f32 v[78:79], v[78:79], v[184:185]
	v_rcp_f32_e32 v76, v76
	v_rcp_f32_e32 v77, v77
	v_rcp_f32_e32 v78, v78
	v_rcp_f32_e32 v79, v79
	v_pk_mul_f32 v[72:73], v[72:73], v[76:77]
	v_pk_mul_f32 v[74:75], v[74:75], v[78:79]
	s_nop 0
	v_pk_mul_f32 v[74:75], v[66:67], v[74:75]
	v_pk_mul_f32 v[66:67], v[64:65], v[72:73]
	v_cvt_pk_bf16_f32 v64, v68, v69
	v_mad_i64_i32 v[68:69], s[14:15], v156, s68, v[112:113]
	v_cvt_pk_bf16_f32 v65, v70, v71
	v_cvt_pk_bf16_f32 v66, v66, v67
	v_cvt_pk_bf16_f32 v67, v74, v75
	v_lshl_add_u64 v[68:69], v[68:69], 0, v[114:115]
	global_store_dwordx4 v[68:69], v[64:67], off
	s_nop 1
	v_pk_mul_f32 v[64:65], v[60:61], s[98:99]
	v_pk_mul_f32 v[66:67], v[62:63], s[98:99]
	v_exp_f32_e32 v64, v64
	v_exp_f32_e32 v65, v65
	v_exp_f32_e32 v66, v66
	v_exp_f32_e32 v67, v67
	v_pk_add_f32 v[64:65], v[64:65], v[184:185]
	v_pk_add_f32 v[66:67], v[66:67], v[184:185]
	v_rcp_f32_e32 v64, v64
	v_rcp_f32_e32 v65, v65
	v_rcp_f32_e32 v66, v66
	v_rcp_f32_e32 v67, v67
	v_pk_mul_f32 v[60:61], v[60:61], v[64:65]
	s_nop 0
	v_pk_mul_f32 v[52:53], v[52:53], v[60:61]
	v_pk_mul_f32 v[62:63], v[62:63], v[66:67]
	v_mul_f32_e32 v60, 0xbfb8aa3b, v56
	v_pk_mul_f32 v[54:55], v[54:55], v[62:63]
	v_mul_f32_e32 v61, 0xbfb8aa3b, v57
	v_pk_mul_f32 v[62:63], v[58:59], s[98:99]
	v_exp_f32_e32 v60, v60
	v_exp_f32_e32 v61, v61
	v_exp_f32_e32 v62, v62
	v_exp_f32_e32 v63, v63
	v_pk_add_f32 v[60:61], v[60:61], v[184:185]
	v_pk_add_f32 v[62:63], v[62:63], v[184:185]
	v_rcp_f32_e32 v60, v60
	v_rcp_f32_e32 v61, v61
	v_rcp_f32_e32 v62, v62
	v_rcp_f32_e32 v63, v63
	v_pk_mul_f32 v[56:57], v[56:57], v[60:61]
	v_pk_mul_f32 v[58:59], v[58:59], v[62:63]
	s_nop 0
	v_pk_mul_f32 v[58:59], v[50:51], v[58:59]
	v_pk_mul_f32 v[50:51], v[48:49], v[56:57]
	v_cvt_pk_bf16_f32 v48, v52, v53
	v_mad_i64_i32 v[52:53], s[14:15], v152, s68, v[112:113]
	v_cvt_pk_bf16_f32 v49, v54, v55
	v_cvt_pk_bf16_f32 v50, v50, v51
	v_cvt_pk_bf16_f32 v51, v58, v59
	v_lshl_add_u64 v[52:53], v[52:53], 0, v[114:115]
	global_store_dwordx4 v[52:53], v[48:51], off
	s_nop 1
	v_pk_mul_f32 v[48:49], v[44:45], s[98:99]
	v_pk_mul_f32 v[50:51], v[46:47], s[98:99]
	v_exp_f32_e32 v48, v48
	v_exp_f32_e32 v49, v49
	v_exp_f32_e32 v50, v50
	v_exp_f32_e32 v51, v51
	v_pk_add_f32 v[48:49], v[48:49], v[184:185]
	v_pk_add_f32 v[50:51], v[50:51], v[184:185]
	v_rcp_f32_e32 v48, v48
	v_rcp_f32_e32 v49, v49
	v_rcp_f32_e32 v50, v50
	v_rcp_f32_e32 v51, v51
	v_pk_mul_f32 v[44:45], v[44:45], v[48:49]
	s_nop 0
	v_pk_mul_f32 v[36:37], v[36:37], v[44:45]
	v_pk_mul_f32 v[46:47], v[46:47], v[50:51]
	v_mul_f32_e32 v44, 0xbfb8aa3b, v40
	v_pk_mul_f32 v[38:39], v[38:39], v[46:47]
	v_mul_f32_e32 v45, 0xbfb8aa3b, v41
	v_pk_mul_f32 v[46:47], v[42:43], s[98:99]
	v_exp_f32_e32 v44, v44
	v_exp_f32_e32 v45, v45
	v_exp_f32_e32 v46, v46
	v_exp_f32_e32 v47, v47
	v_pk_add_f32 v[44:45], v[44:45], v[184:185]
	v_pk_add_f32 v[46:47], v[46:47], v[184:185]
	v_rcp_f32_e32 v44, v44
	v_rcp_f32_e32 v45, v45
	v_rcp_f32_e32 v46, v46
	v_rcp_f32_e32 v47, v47
	v_pk_mul_f32 v[40:41], v[40:41], v[44:45]
	v_pk_mul_f32 v[42:43], v[42:43], v[46:47]
	s_nop 0
	v_pk_mul_f32 v[42:43], v[34:35], v[42:43]
	v_pk_mul_f32 v[34:35], v[32:33], v[40:41]
	v_cvt_pk_bf16_f32 v32, v36, v37
	v_mad_i64_i32 v[36:37], s[14:15], v150, s68, v[112:113]
	v_cvt_pk_bf16_f32 v33, v38, v39
	v_cvt_pk_bf16_f32 v34, v34, v35
	v_cvt_pk_bf16_f32 v35, v42, v43
	v_lshl_add_u64 v[36:37], v[36:37], 0, v[114:115]
	global_store_dwordx4 v[36:37], v[32:35], off
	s_nop 1
	v_pk_mul_f32 v[32:33], v[28:29], s[98:99]
	v_pk_mul_f32 v[34:35], v[30:31], s[98:99]
	v_exp_f32_e32 v32, v32
	v_exp_f32_e32 v33, v33
	v_exp_f32_e32 v34, v34
	v_exp_f32_e32 v35, v35
	v_pk_add_f32 v[32:33], v[32:33], v[184:185]
	v_pk_add_f32 v[34:35], v[34:35], v[184:185]
	v_rcp_f32_e32 v32, v32
	v_rcp_f32_e32 v33, v33
	v_rcp_f32_e32 v34, v34
	v_rcp_f32_e32 v35, v35
	v_pk_mul_f32 v[28:29], v[28:29], v[32:33]
	s_nop 0
	v_pk_mul_f32 v[20:21], v[20:21], v[28:29]
	v_pk_mul_f32 v[30:31], v[30:31], v[34:35]
	v_mul_f32_e32 v28, 0xbfb8aa3b, v24
	v_pk_mul_f32 v[22:23], v[22:23], v[30:31]
	v_mul_f32_e32 v29, 0xbfb8aa3b, v25
	v_pk_mul_f32 v[30:31], v[26:27], s[98:99]
	v_exp_f32_e32 v28, v28
	v_exp_f32_e32 v29, v29
	v_exp_f32_e32 v30, v30
	v_exp_f32_e32 v31, v31
	v_pk_add_f32 v[28:29], v[28:29], v[184:185]
	v_pk_add_f32 v[30:31], v[30:31], v[184:185]
	v_rcp_f32_e32 v28, v28
	v_rcp_f32_e32 v29, v29
	v_rcp_f32_e32 v30, v30
	v_rcp_f32_e32 v31, v31
	v_pk_mul_f32 v[24:25], v[24:25], v[28:29]
	v_pk_mul_f32 v[26:27], v[26:27], v[30:31]
	s_nop 0
	v_pk_mul_f32 v[26:27], v[18:19], v[26:27]
	v_pk_mul_f32 v[18:19], v[16:17], v[24:25]
	v_cvt_pk_bf16_f32 v16, v20, v21
	v_mad_i64_i32 v[20:21], s[14:15], v148, s68, v[112:113]
	v_cvt_pk_bf16_f32 v17, v22, v23
	v_cvt_pk_bf16_f32 v18, v18, v19
	v_cvt_pk_bf16_f32 v19, v26, v27
	v_lshl_add_u64 v[20:21], v[20:21], 0, v[114:115]
	global_store_dwordx4 v[20:21], v[16:19], off
	s_nop 1
	v_pk_mul_f32 v[16:17], v[12:13], s[98:99]
	v_pk_mul_f32 v[18:19], v[14:15], s[98:99]
	v_exp_f32_e32 v16, v16
	v_exp_f32_e32 v17, v17
	v_exp_f32_e32 v18, v18
	v_exp_f32_e32 v19, v19
	v_pk_add_f32 v[16:17], v[16:17], v[184:185]
	v_pk_add_f32 v[18:19], v[18:19], v[184:185]
	v_rcp_f32_e32 v16, v16
	v_rcp_f32_e32 v17, v17
	v_rcp_f32_e32 v18, v18
	v_rcp_f32_e32 v19, v19
	v_pk_mul_f32 v[12:13], v[12:13], v[16:17]
	s_nop 0
	v_pk_mul_f32 v[4:5], v[4:5], v[12:13]
	v_pk_mul_f32 v[14:15], v[14:15], v[18:19]
	v_mul_f32_e32 v12, 0xbfb8aa3b, v8
	v_pk_mul_f32 v[6:7], v[6:7], v[14:15]
	v_mul_f32_e32 v13, 0xbfb8aa3b, v9
	v_pk_mul_f32 v[14:15], v[10:11], s[98:99]
	v_exp_f32_e32 v12, v12
	v_exp_f32_e32 v13, v13
	v_exp_f32_e32 v14, v14
	v_exp_f32_e32 v15, v15
	v_pk_add_f32 v[12:13], v[12:13], v[184:185]
	v_pk_add_f32 v[14:15], v[14:15], v[184:185]
	v_rcp_f32_e32 v12, v12
	v_rcp_f32_e32 v13, v13
	v_rcp_f32_e32 v14, v14
	v_rcp_f32_e32 v15, v15
	v_pk_mul_f32 v[8:9], v[8:9], v[12:13]
	v_pk_mul_f32 v[10:11], v[10:11], v[14:15]
	s_nop 0
	v_pk_mul_f32 v[10:11], v[2:3], v[10:11]
	v_pk_mul_f32 v[2:3], v[0:1], v[8:9]
	v_cvt_pk_bf16_f32 v0, v4, v5
	v_mad_i64_i32 v[4:5], s[14:15], v146, s68, v[112:113]
	v_lshl_add_u64 v[4:5], v[4:5], 0, v[114:115]
	v_cvt_pk_bf16_f32 v1, v6, v7
	v_cvt_pk_bf16_f32 v2, v2, v3
	v_cvt_pk_bf16_f32 v3, v10, v11
	global_store_dwordx4 v[4:5], v[0:3], off
	s_cbranch_vccnz .LBB0_992
	s_andn2_b64 vcc, exec, s[18:19]
	s_cbranch_vccnz .LBB0_991
	s_barrier
	s_branch .LBB0_991

; __device__ __forceinline__ unsigned cvt_pk_bf16(float lo, float hi) { unsigned r; asm volatile("v_cvt_pk_bf16_f32 %0, %1, %2" : "=v"(r) : "v"(lo), "v"(hi)); return r; }
; __device__ __forceinline__ float silu_f(float v) { return v * __builtin_amdgcn_rcpf(1.0f + __builtin_amdgcn_exp2f(v * -1.4426950408889634f)); }
; __device__ __forceinline__ f32x4 silu4(f32x4 v) { return (f32x4){silu_f(v[0]), silu_f(v[1]), silu_f(v[2]), silu_f(v[3])}; }
; __device__ __forceinline__ float sq4(f32x4 v) { return (v[0] * v[0] + v[1] * v[1]) + (v[2] * v[2] + v[3] * v[3]); }
; __device__ __forceinline__ u32x4 pack8(f32x4 a, f32x4 b) { u32x4 w; w.x = cvt_pk_bf16(a[0], a[1]); w.y = cvt_pk_bf16(a[2], a[3]); w.z = cvt_pk_bf16(b[0], b[1]); w.w = cvt_pk_bf16(b[2], b[3]); return w; }
;     __device__ __forceinline__ void operator()(const f32x4 (&acc)[2][2][4][2], const Unit& u, int wr, int wc, int fr, int fq) const {
;     ...
;         for (int ai = 0; ai < 2; ++ai)
; #pragma unroll
;             for (int m = 0; m < 4; ++m) {
;                 const int row = u.pm * BM + ai * HALF + wr * 64 + m * 16 + fr;
;                 const float rstd = rs[ai][m];
;                 const f32x4 a0 = silu4(acc[ai][0][m][0] * rstd) * (acc[ai][1][m][0] * rstd);
;                 const f32x4 a1 = silu4(acc[ai][0][m][1] * rstd) * (acc[ai][1][m][1] * rstd);
;                 *(u32x4*)(ACT + (size_t)row * 2816 + col0) = pack8(a0, a1);
;             }
.Lrsj_2:
	s_mov_b32 s98, 0xbfb8aa3b
	s_mov_b32 s99, 0xbfb8aa3b
	v_mov_b32_e32 v212, 1.0
	v_mov_b32_e32 v213, 1.0
	v_mul_f32_e32 v147, 0xbfb8aa3b, v124
	v_exp_f32_e32 v147, v147
	v_mul_f32_e32 v149, 0xbfb8aa3b, v125
	v_exp_f32_e32 v149, v149
	v_pk_mul_f32 v[126:127], v[126:127], v[176:177] op_sel_hi:[1,0]
	v_add_f32_e32 v147, 1.0, v147
	v_rcp_f32_e32 v178, v147
	v_add_f32_e32 v147, 1.0, v149
	v_mul_f32_e32 v149, 0xbfb8aa3b, v126
	v_exp_f32_e32 v149, v149
	v_mul_f32_e32 v151, 0xbfb8aa3b, v127
	v_exp_f32_e32 v151, v151
	v_rcp_f32_e32 v179, v147
	v_add_f32_e32 v147, 1.0, v149
	v_rcp_f32_e32 v180, v147
	v_add_f32_e32 v147, 1.0, v151
	v_pk_mul_f32 v[120:121], v[120:121], v[176:177] op_sel_hi:[1,0]
	v_rcp_f32_e32 v181, v147
	v_mul_f32_e32 v147, 0xbfb8aa3b, v120
	v_exp_f32_e32 v147, v147
	v_mul_f32_e32 v149, 0xbfb8aa3b, v121
	v_exp_f32_e32 v149, v149
	v_pk_mul_f32 v[122:123], v[122:123], v[176:177] op_sel_hi:[1,0]
	v_add_f32_e32 v147, 1.0, v147
	v_pk_mul_f32 v[124:125], v[124:125], v[178:179]
	v_rcp_f32_e32 v178, v147
	v_add_f32_e32 v147, 1.0, v149
	v_mul_f32_e32 v149, 0xbfb8aa3b, v122
	v_exp_f32_e32 v149, v149
	v_mul_f32_e32 v151, 0xbfb8aa3b, v123
	v_exp_f32_e32 v151, v151
	v_rcp_f32_e32 v179, v147
	v_add_f32_e32 v147, 1.0, v149
	v_pk_mul_f32 v[126:127], v[126:127], v[180:181]
	v_rcp_f32_e32 v180, v147
	v_add_f32_e32 v147, 1.0, v151
	v_rcp_f32_e32 v181, v147
	v_pk_mul_f32 v[116:117], v[116:117], v[176:177] op_sel_hi:[1,0]
	v_pk_mul_f32 v[118:119], v[118:119], v[176:177] op_sel_hi:[1,0]
	v_pk_mul_f32 v[120:121], v[120:121], v[178:179]
	v_pk_mul_f32 v[112:113], v[112:113], v[176:177] op_sel_hi:[1,0]
	v_lshl_or_b32 v182, s61, 7, v161
	v_pk_mul_f32 v[118:119], v[118:119], v[126:127]
	v_pk_mul_f32 v[116:117], v[116:117], v[124:125]
	v_pk_mul_f32 v[122:123], v[122:123], v[180:181]
	v_pk_mul_f32 v[114:115], v[114:115], v[176:177] op_sel_hi:[1,0]
	v_pk_mul_f32 v[112:113], v[112:113], v[120:121]
	v_ashrrev_i32_e32 v183, 31, v182
	v_pk_mul_f32 v[114:115], v[114:115], v[122:123]
	v_cvt_pk_bf16_f32 v116, v116, v117
	v_cvt_pk_bf16_f32 v117, v118, v119
	v_cvt_pk_bf16_f32 v118, v112, v113
	v_mov_b64_e32 v[112:113], s[16:17]
	v_cvt_pk_bf16_f32 v119, v114, v115
	v_mad_i64_i32 v[120:121], s[46:47], v170, s60, v[112:113]
	v_lshlrev_b64 v[114:115], 1, v[182:183]
	v_pk_mul_f32 v[108:109], v[108:109], v[174:175] op_sel_hi:[1,0]
	v_pk_mul_f32 v[110:111], v[110:111], v[174:175] op_sel_hi:[1,0]
	v_pk_mul_f32 v[122:123], v[108:109], s[98:99]
	v_lshl_add_u64 v[120:121], v[120:121], 0, v[114:115]
	v_pk_mul_f32 v[104:105], v[104:105], v[174:175] op_sel_hi:[1,0]
	v_pk_mul_f32 v[106:107], v[106:107], v[174:175] op_sel_hi:[1,0]
	v_exp_f32_e32 v122, v122
	v_exp_f32_e32 v123, v123
	v_pk_mul_f32 v[124:125], v[110:111], s[98:99]
	global_store_dwordx4 v[120:121], v[116:119], off
	v_exp_f32_e32 v124, v124
	v_exp_f32_e32 v125, v125
	v_pk_mul_f32 v[116:117], v[104:105], s[98:99]
	v_pk_mul_f32 v[118:119], v[106:107], s[98:99]
	v_exp_f32_e32 v116, v116
	v_exp_f32_e32 v117, v117
	v_exp_f32_e32 v118, v118
	v_exp_f32_e32 v119, v119
	v_pk_add_f32 v[122:123], v[122:123], v[212:213]
	v_rcp_f32_e32 v122, v122
	v_rcp_f32_e32 v123, v123
	v_pk_add_f32 v[124:125], v[124:125], v[212:213]
	v_pk_add_f32 v[116:117], v[116:117], v[212:213]
	v_pk_add_f32 v[118:119], v[118:119], v[212:213]
	v_rcp_f32_e32 v124, v124
	v_rcp_f32_e32 v125, v125
	v_rcp_f32_e32 v116, v116
	v_rcp_f32_e32 v117, v117
	v_rcp_f32_e32 v118, v118
	v_rcp_f32_e32 v119, v119
	v_pk_mul_f32 v[108:109], v[108:109], v[122:123]
	v_pk_mul_f32 v[100:101], v[100:101], v[174:175] op_sel_hi:[1,0]
	v_pk_mul_f32 v[110:111], v[110:111], v[124:125]
	v_pk_mul_f32 v[102:103], v[102:103], v[174:175] op_sel_hi:[1,0]
	v_pk_mul_f32 v[100:101], v[100:101], v[108:109]
	v_pk_mul_f32 v[104:105], v[104:105], v[116:117]
	v_pk_mul_f32 v[106:107], v[106:107], v[118:119]
	v_pk_mul_f32 v[96:97], v[96:97], v[174:175] op_sel_hi:[1,0]
	v_pk_mul_f32 v[98:99], v[98:99], v[174:175] op_sel_hi:[1,0]
	v_pk_mul_f32 v[102:103], v[102:103], v[110:111]
	v_pk_mul_f32 v[106:107], v[98:99], v[106:107]
	v_pk_mul_f32 v[98:99], v[96:97], v[104:105]
	v_cvt_pk_bf16_f32 v96, v100, v101
	v_mad_i64_i32 v[100:101], s[46:47], v166, s60, v[112:113]
	v_pk_mul_f32 v[92:93], v[92:93], v[172:173] op_sel_hi:[1,0]
	v_cvt_pk_bf16_f32 v97, v102, v103
	v_cvt_pk_bf16_f32 v98, v98, v99
	v_cvt_pk_bf16_f32 v99, v106, v107
	v_pk_mul_f32 v[94:95], v[94:95], v[172:173] op_sel_hi:[1,0]
	v_pk_mul_f32 v[102:103], v[92:93], s[98:99]
	v_lshl_add_u64 v[100:101], v[100:101], 0, v[114:115]
	v_pk_mul_f32 v[88:89], v[88:89], v[172:173] op_sel_hi:[1,0]
	v_pk_mul_f32 v[90:91], v[90:91], v[172:173] op_sel_hi:[1,0]
	v_exp_f32_e32 v102, v102
	v_exp_f32_e32 v103, v103
	v_pk_mul_f32 v[104:105], v[94:95], s[98:99]
	global_store_dwordx4 v[100:101], v[96:99], off
	v_exp_f32_e32 v104, v104
	v_exp_f32_e32 v105, v105
	v_pk_mul_f32 v[96:97], v[88:89], s[98:99]
	v_pk_mul_f32 v[98:99], v[90:91], s[98:99]
	v_exp_f32_e32 v96, v96
	v_exp_f32_e32 v97, v97
	v_exp_f32_e32 v98, v98
	v_exp_f32_e32 v99, v99
	v_pk_add_f32 v[102:103], v[102:103], v[212:213]
	v_rcp_f32_e32 v102, v102
	v_rcp_f32_e32 v103, v103
	v_pk_add_f32 v[104:105], v[104:105], v[212:213]
	v_pk_add_f32 v[96:97], v[96:97], v[212:213]
	v_pk_add_f32 v[98:99], v[98:99], v[212:213]
	v_rcp_f32_e32 v104, v104
	v_rcp_f32_e32 v105, v105
	v_rcp_f32_e32 v96, v96
	v_rcp_f32_e32 v97, v97
	v_rcp_f32_e32 v98, v98
	v_rcp_f32_e32 v99, v99
	v_pk_mul_f32 v[92:93], v[92:93], v[102:103]
	v_pk_mul_f32 v[84:85], v[84:85], v[172:173] op_sel_hi:[1,0]
	v_pk_mul_f32 v[94:95], v[94:95], v[104:105]
	v_pk_mul_f32 v[86:87], v[86:87], v[172:173] op_sel_hi:[1,0]
	v_pk_mul_f32 v[84:85], v[84:85], v[92:93]
; __device__ __forceinline__ unsigned cvt_pk_bf16(float lo, float hi) { unsigned r; asm volatile("v_cvt_pk_bf16_f32 %0, %1, %2" : "=v"(r) : "v"(lo), "v"(hi)); return r; }
; __device__ __forceinline__ float silu_f(float v) { return v * __builtin_amdgcn_rcpf(1.0f + __builtin_amdgcn_exp2f(v * -1.4426950408889634f)); }
; __device__ __forceinline__ f32x4 silu4(f32x4 v) { return (f32x4){silu_f(v[0]), silu_f(v[1]), silu_f(v[2]), silu_f(v[3])}; }
; __device__ __forceinline__ float sq4(f32x4 v) { return (v[0] * v[0] + v[1] * v[1]) + (v[2] * v[2] + v[3] * v[3]); }
; __device__ __forceinline__ u32x4 pack8(f32x4 a, f32x4 b) { u32x4 w; w.x = cvt_pk_bf16(a[0], a[1]); w.y = cvt_pk_bf16(a[2], a[3]); w.z = cvt_pk_bf16(b[0], b[1]); w.w = cvt_pk_bf16(b[2], b[3]); return w; }
;     __device__ __forceinline__ void operator()(const f32x4 (&acc)[2][2][4][2], const Unit& u, int wr, int wc, int fr, int fq) const {
;     ...
;         for (int ai = 0; ai < 2; ++ai)
; #pragma unroll
;             for (int m = 0; m < 4; ++m) {
;                 const int row = u.pm * BM + ai * HALF + wr * 64 + m * 16 + fr;
;                 const float rstd = rs[ai][m];
;                 const f32x4 a0 = silu4(acc[ai][0][m][0] * rstd) * (acc[ai][1][m][0] * rstd);
;                 const f32x4 a1 = silu4(acc[ai][0][m][1] * rstd) * (acc[ai][1][m][1] * rstd);
;                 *(u32x4*)(ACT + (size_t)row * 2816 + col0) = pack8(a0, a1);
;             }
	v_pk_mul_f32 v[88:89], v[88:89], v[96:97]
	v_pk_mul_f32 v[90:91], v[90:91], v[98:99]
	v_pk_mul_f32 v[80:81], v[80:81], v[172:173] op_sel_hi:[1,0]
	v_pk_mul_f32 v[82:83], v[82:83], v[172:173] op_sel_hi:[1,0]
	v_pk_mul_f32 v[86:87], v[86:87], v[94:95]
	v_pk_mul_f32 v[90:91], v[82:83], v[90:91]
	v_pk_mul_f32 v[82:83], v[80:81], v[88:89]
	v_cvt_pk_bf16_f32 v80, v84, v85
	v_mad_i64_i32 v[84:85], s[46:47], v162, s60, v[112:113]
	v_pk_mul_f32 v[76:77], v[76:77], v[168:169] op_sel_hi:[1,0]
	v_cvt_pk_bf16_f32 v81, v86, v87
	v_cvt_pk_bf16_f32 v82, v82, v83
	v_cvt_pk_bf16_f32 v83, v90, v91
	v_pk_mul_f32 v[78:79], v[78:79], v[168:169] op_sel_hi:[1,0]
	v_pk_mul_f32 v[86:87], v[76:77], s[98:99]
	v_lshl_add_u64 v[84:85], v[84:85], 0, v[114:115]
	v_pk_mul_f32 v[72:73], v[72:73], v[168:169] op_sel_hi:[1,0]
	v_pk_mul_f32 v[74:75], v[74:75], v[168:169] op_sel_hi:[1,0]
	v_exp_f32_e32 v86, v86
	v_exp_f32_e32 v87, v87
	v_pk_mul_f32 v[88:89], v[78:79], s[98:99]
	global_store_dwordx4 v[84:85], v[80:83], off
	v_exp_f32_e32 v88, v88
	v_exp_f32_e32 v89, v89
	v_pk_mul_f32 v[80:81], v[72:73], s[98:99]
	v_pk_mul_f32 v[82:83], v[74:75], s[98:99]
	v_exp_f32_e32 v80, v80
	v_exp_f32_e32 v81, v81
	v_exp_f32_e32 v82, v82
	v_exp_f32_e32 v83, v83
	v_pk_add_f32 v[86:87], v[86:87], v[212:213]
	v_rcp_f32_e32 v86, v86
	v_rcp_f32_e32 v87, v87
	v_pk_add_f32 v[88:89], v[88:89], v[212:213]
	v_pk_add_f32 v[80:81], v[80:81], v[212:213]
	v_pk_add_f32 v[82:83], v[82:83], v[212:213]
	v_rcp_f32_e32 v88, v88
	v_rcp_f32_e32 v89, v89
	v_rcp_f32_e32 v80, v80
	v_rcp_f32_e32 v81, v81
	v_rcp_f32_e32 v82, v82
	v_rcp_f32_e32 v83, v83
	v_pk_mul_f32 v[76:77], v[76:77], v[86:87]
	v_pk_mul_f32 v[68:69], v[68:69], v[168:169] op_sel_hi:[1,0]
	v_pk_mul_f32 v[78:79], v[78:79], v[88:89]
	v_pk_mul_f32 v[70:71], v[70:71], v[168:169] op_sel_hi:[1,0]
	v_pk_mul_f32 v[68:69], v[68:69], v[76:77]
	v_pk_mul_f32 v[72:73], v[72:73], v[80:81]
	v_pk_mul_f32 v[74:75], v[74:75], v[82:83]
	v_pk_mul_f32 v[64:65], v[64:65], v[168:169] op_sel_hi:[1,0]
	v_pk_mul_f32 v[66:67], v[66:67], v[168:169] op_sel_hi:[1,0]
	v_pk_mul_f32 v[70:71], v[70:71], v[78:79]
	v_pk_mul_f32 v[74:75], v[66:67], v[74:75]
	v_pk_mul_f32 v[66:67], v[64:65], v[72:73]
	v_cvt_pk_bf16_f32 v64, v68, v69
	v_mad_i64_i32 v[68:69], s[46:47], v158, s60, v[112:113]
	v_pk_mul_f32 v[60:61], v[60:61], v[164:165] op_sel_hi:[1,0]
	v_cvt_pk_bf16_f32 v65, v70, v71
	v_cvt_pk_bf16_f32 v66, v66, v67
	v_cvt_pk_bf16_f32 v67, v74, v75
	v_pk_mul_f32 v[62:63], v[62:63], v[164:165] op_sel_hi:[1,0]
	v_pk_mul_f32 v[70:71], v[60:61], s[98:99]
	v_lshl_add_u64 v[68:69], v[68:69], 0, v[114:115]
	v_pk_mul_f32 v[56:57], v[56:57], v[164:165] op_sel_hi:[1,0]
	v_pk_mul_f32 v[58:59], v[58:59], v[164:165] op_sel_hi:[1,0]
	v_exp_f32_e32 v70, v70
	v_exp_f32_e32 v71, v71
	v_pk_mul_f32 v[72:73], v[62:63], s[98:99]
	global_store_dwordx4 v[68:69], v[64:67], off
	v_exp_f32_e32 v72, v72
	v_exp_f32_e32 v73, v73
	v_pk_mul_f32 v[64:65], v[56:57], s[98:99]
	v_pk_mul_f32 v[66:67], v[58:59], s[98:99]
	v_exp_f32_e32 v64, v64
	v_exp_f32_e32 v65, v65
	v_exp_f32_e32 v66, v66
	v_exp_f32_e32 v67, v67
	v_pk_add_f32 v[70:71], v[70:71], v[212:213]
	v_rcp_f32_e32 v70, v70
	v_rcp_f32_e32 v71, v71
	v_pk_add_f32 v[72:73], v[72:73], v[212:213]
	v_pk_add_f32 v[64:65], v[64:65], v[212:213]
	v_pk_add_f32 v[66:67], v[66:67], v[212:213]
	v_rcp_f32_e32 v72, v72
	v_rcp_f32_e32 v73, v73
	v_rcp_f32_e32 v64, v64
	v_rcp_f32_e32 v65, v65
	v_rcp_f32_e32 v66, v66
	v_rcp_f32_e32 v67, v67
	v_pk_mul_f32 v[60:61], v[60:61], v[70:71]
	v_pk_mul_f32 v[52:53], v[52:53], v[164:165] op_sel_hi:[1,0]
	v_pk_mul_f32 v[62:63], v[62:63], v[72:73]
	v_pk_mul_f32 v[54:55], v[54:55], v[164:165] op_sel_hi:[1,0]
	v_pk_mul_f32 v[52:53], v[52:53], v[60:61]
	v_pk_mul_f32 v[56:57], v[56:57], v[64:65]
	v_pk_mul_f32 v[58:59], v[58:59], v[66:67]
	v_pk_mul_f32 v[48:49], v[48:49], v[164:165] op_sel_hi:[1,0]
	v_pk_mul_f32 v[50:51], v[50:51], v[164:165] op_sel_hi:[1,0]
	v_pk_mul_f32 v[54:55], v[54:55], v[62:63]
	v_pk_mul_f32 v[58:59], v[50:51], v[58:59]
	v_pk_mul_f32 v[50:51], v[48:49], v[56:57]
	v_cvt_pk_bf16_f32 v48, v52, v53
	v_mad_i64_i32 v[52:53], s[46:47], v154, s60, v[112:113]
	v_pk_mul_f32 v[44:45], v[44:45], v[160:161] op_sel_hi:[1,0]
	v_cvt_pk_bf16_f32 v49, v54, v55
	v_cvt_pk_bf16_f32 v50, v50, v51
	v_cvt_pk_bf16_f32 v51, v58, v59
	v_pk_mul_f32 v[46:47], v[46:47], v[160:161] op_sel_hi:[1,0]
	v_pk_mul_f32 v[54:55], v[44:45], s[98:99]
	v_lshl_add_u64 v[52:53], v[52:53], 0, v[114:115]
	v_pk_mul_f32 v[40:41], v[40:41], v[160:161] op_sel_hi:[1,0]
	v_pk_mul_f32 v[42:43], v[42:43], v[160:161] op_sel_hi:[1,0]
	v_exp_f32_e32 v54, v54
	v_exp_f32_e32 v55, v55
	v_pk_mul_f32 v[56:57], v[46:47], s[98:99]
	global_store_dwordx4 v[52:53], v[48:51], off
	v_exp_f32_e32 v56, v56
	v_exp_f32_e32 v57, v57
	v_pk_mul_f32 v[48:49], v[40:41], s[98:99]
	v_pk_mul_f32 v[50:51], v[42:43], s[98:99]
	v_exp_f32_e32 v48, v48
	v_exp_f32_e32 v49, v49
	v_exp_f32_e32 v50, v50
	v_exp_f32_e32 v51, v51
	v_pk_add_f32 v[54:55], v[54:55], v[212:213]
; __device__ __forceinline__ unsigned cvt_pk_bf16(float lo, float hi) { unsigned r; asm volatile("v_cvt_pk_bf16_f32 %0, %1, %2" : "=v"(r) : "v"(lo), "v"(hi)); return r; }
; __device__ __forceinline__ float silu_f(float v) { return v * __builtin_amdgcn_rcpf(1.0f + __builtin_amdgcn_exp2f(v * -1.4426950408889634f)); }
; __device__ __forceinline__ f32x4 silu4(f32x4 v) { return (f32x4){silu_f(v[0]), silu_f(v[1]), silu_f(v[2]), silu_f(v[3])}; }
; __device__ __forceinline__ float sq4(f32x4 v) { return (v[0] * v[0] + v[1] * v[1]) + (v[2] * v[2] + v[3] * v[3]); }
; __device__ __forceinline__ u32x4 pack8(f32x4 a, f32x4 b) { u32x4 w; w.x = cvt_pk_bf16(a[0], a[1]); w.y = cvt_pk_bf16(a[2], a[3]); w.z = cvt_pk_bf16(b[0], b[1]); w.w = cvt_pk_bf16(b[2], b[3]); return w; }
;     __device__ __forceinline__ void operator()(const f32x4 (&acc)[2][2][4][2], const Unit& u, int wr, int wc, int fr, int fq) const {
;     ...
;         for (int ai = 0; ai < 2; ++ai)
; #pragma unroll
;             for (int m = 0; m < 4; ++m) {
;                 const int row = u.pm * BM + ai * HALF + wr * 64 + m * 16 + fr;
;                 const float rstd = rs[ai][m];
;                 const f32x4 a0 = silu4(acc[ai][0][m][0] * rstd) * (acc[ai][1][m][0] * rstd);
;                 const f32x4 a1 = silu4(acc[ai][0][m][1] * rstd) * (acc[ai][1][m][1] * rstd);
;                 *(u32x4*)(ACT + (size_t)row * 2816 + col0) = pack8(a0, a1);
;             }
	v_rcp_f32_e32 v54, v54
	v_rcp_f32_e32 v55, v55
	v_pk_add_f32 v[56:57], v[56:57], v[212:213]
	v_pk_add_f32 v[48:49], v[48:49], v[212:213]
	v_pk_add_f32 v[50:51], v[50:51], v[212:213]
	v_rcp_f32_e32 v56, v56
	v_rcp_f32_e32 v57, v57
	v_rcp_f32_e32 v48, v48
	v_rcp_f32_e32 v49, v49
	v_rcp_f32_e32 v50, v50
	v_rcp_f32_e32 v51, v51
	v_pk_mul_f32 v[44:45], v[44:45], v[54:55]
	v_pk_mul_f32 v[36:37], v[36:37], v[160:161] op_sel_hi:[1,0]
	v_pk_mul_f32 v[46:47], v[46:47], v[56:57]
	v_pk_mul_f32 v[38:39], v[38:39], v[160:161] op_sel_hi:[1,0]
	v_pk_mul_f32 v[36:37], v[36:37], v[44:45]
	v_pk_mul_f32 v[40:41], v[40:41], v[48:49]
	v_pk_mul_f32 v[42:43], v[42:43], v[50:51]
	v_pk_mul_f32 v[32:33], v[32:33], v[160:161] op_sel_hi:[1,0]
	v_pk_mul_f32 v[34:35], v[34:35], v[160:161] op_sel_hi:[1,0]
	v_pk_mul_f32 v[38:39], v[38:39], v[46:47]
	v_pk_mul_f32 v[42:43], v[34:35], v[42:43]
	v_pk_mul_f32 v[34:35], v[32:33], v[40:41]
	v_cvt_pk_bf16_f32 v32, v36, v37
	v_mad_i64_i32 v[36:37], s[46:47], v150, s60, v[112:113]
	v_pk_mul_f32 v[28:29], v[28:29], v[156:157] op_sel_hi:[1,0]
	v_cvt_pk_bf16_f32 v33, v38, v39
	v_cvt_pk_bf16_f32 v34, v34, v35
	v_cvt_pk_bf16_f32 v35, v42, v43
	v_pk_mul_f32 v[30:31], v[30:31], v[156:157] op_sel_hi:[1,0]
	v_pk_mul_f32 v[38:39], v[28:29], s[98:99]
	v_lshl_add_u64 v[36:37], v[36:37], 0, v[114:115]
	v_pk_mul_f32 v[24:25], v[24:25], v[156:157] op_sel_hi:[1,0]
	v_pk_mul_f32 v[26:27], v[26:27], v[156:157] op_sel_hi:[1,0]
	v_exp_f32_e32 v38, v38
	v_exp_f32_e32 v39, v39
	v_pk_mul_f32 v[40:41], v[30:31], s[98:99]
	global_store_dwordx4 v[36:37], v[32:35], off
	v_exp_f32_e32 v40, v40
	v_exp_f32_e32 v41, v41
	v_pk_mul_f32 v[32:33], v[24:25], s[98:99]
	v_pk_mul_f32 v[34:35], v[26:27], s[98:99]
	v_exp_f32_e32 v32, v32
	v_exp_f32_e32 v33, v33
	v_exp_f32_e32 v34, v34
	v_exp_f32_e32 v35, v35
	v_pk_add_f32 v[38:39], v[38:39], v[212:213]
	v_rcp_f32_e32 v38, v38
	v_rcp_f32_e32 v39, v39
	v_pk_add_f32 v[40:41], v[40:41], v[212:213]
	v_pk_add_f32 v[32:33], v[32:33], v[212:213]
	v_pk_add_f32 v[34:35], v[34:35], v[212:213]
	v_rcp_f32_e32 v40, v40
	v_rcp_f32_e32 v41, v41
	v_rcp_f32_e32 v32, v32
	v_rcp_f32_e32 v33, v33
	v_rcp_f32_e32 v34, v34
	v_rcp_f32_e32 v35, v35
	v_pk_mul_f32 v[28:29], v[28:29], v[38:39]
	v_pk_mul_f32 v[20:21], v[20:21], v[156:157] op_sel_hi:[1,0]
	v_pk_mul_f32 v[30:31], v[30:31], v[40:41]
	v_pk_mul_f32 v[22:23], v[22:23], v[156:157] op_sel_hi:[1,0]
	v_pk_mul_f32 v[20:21], v[20:21], v[28:29]
	v_pk_mul_f32 v[24:25], v[24:25], v[32:33]
	v_pk_mul_f32 v[26:27], v[26:27], v[34:35]
	v_pk_mul_f32 v[16:17], v[16:17], v[156:157] op_sel_hi:[1,0]
	v_pk_mul_f32 v[18:19], v[18:19], v[156:157] op_sel_hi:[1,0]
	v_pk_mul_f32 v[22:23], v[22:23], v[30:31]
	v_pk_mul_f32 v[26:27], v[18:19], v[26:27]
	v_pk_mul_f32 v[18:19], v[16:17], v[24:25]
	v_cvt_pk_bf16_f32 v16, v20, v21
	v_mad_i64_i32 v[20:21], s[46:47], v148, s60, v[112:113]
	v_pk_mul_f32 v[12:13], v[12:13], v[152:153] op_sel_hi:[1,0]
	v_cvt_pk_bf16_f32 v17, v22, v23
	v_cvt_pk_bf16_f32 v18, v18, v19
	v_cvt_pk_bf16_f32 v19, v26, v27
	v_lshl_add_u64 v[20:21], v[20:21], 0, v[114:115]
	v_pk_mul_f32 v[22:23], v[12:13], s[98:99]
	v_pk_mul_f32 v[8:9], v[8:9], v[152:153] op_sel_hi:[1,0]
	v_pk_mul_f32 v[10:11], v[10:11], v[152:153] op_sel_hi:[1,0]
	v_exp_f32_e32 v22, v22
	v_exp_f32_e32 v23, v23
	global_store_dwordx4 v[20:21], v[16:19], off
	v_pk_mul_f32 v[14:15], v[14:15], v[152:153] op_sel_hi:[1,0]
	v_add_f32_e32 v22, 1.0, v22
	v_pk_mul_f32 v[16:17], v[8:9], s[98:99]
	v_pk_mul_f32 v[18:19], v[10:11], s[98:99]
	v_exp_f32_e32 v16, v16
	v_exp_f32_e32 v17, v17
	v_exp_f32_e32 v18, v18
	v_exp_f32_e32 v19, v19
	v_pk_mul_f32 v[24:25], v[14:15], s[98:99]
	v_exp_f32_e32 v24, v24
	v_exp_f32_e32 v25, v25
	v_add_f32_e32 v23, 1.0, v23
	v_rcp_f32_e32 v22, v22
	v_rcp_f32_e32 v23, v23
	v_pk_add_f32 v[16:17], v[16:17], v[212:213]
	v_pk_add_f32 v[18:19], v[18:19], v[212:213]
	v_rcp_f32_e32 v16, v16
	v_rcp_f32_e32 v17, v17
	v_rcp_f32_e32 v18, v18
	v_rcp_f32_e32 v19, v19
	v_pk_add_f32 v[24:25], v[24:25], v[212:213]
	v_rcp_f32_e32 v24, v24
	v_rcp_f32_e32 v25, v25
	v_pk_mul_f32 v[12:13], v[12:13], v[22:23]
	v_pk_mul_f32 v[4:5], v[4:5], v[152:153] op_sel_hi:[1,0]
	v_pk_mul_f32 v[8:9], v[8:9], v[16:17]
	v_pk_mul_f32 v[4:5], v[4:5], v[12:13]
	v_pk_mul_f32 v[10:11], v[10:11], v[18:19]
	v_pk_mul_f32 v[0:1], v[0:1], v[152:153] op_sel_hi:[1,0]
	v_pk_mul_f32 v[2:3], v[2:3], v[152:153] op_sel_hi:[1,0]
	v_pk_mul_f32 v[14:15], v[14:15], v[24:25]
	v_pk_mul_f32 v[10:11], v[2:3], v[10:11]
	v_pk_mul_f32 v[2:3], v[0:1], v[8:9]
	v_cvt_pk_bf16_f32 v0, v4, v5
	v_mad_i64_i32 v[4:5], s[46:47], v146, s60, v[112:113]
	v_pk_mul_f32 v[6:7], v[6:7], v[152:153] op_sel_hi:[1,0]
	v_lshl_add_u64 v[4:5], v[4:5], 0, v[114:115]
	v_pk_mul_f32 v[6:7], v[6:7], v[14:15]
	s_nop 0
	v_cvt_pk_bf16_f32 v1, v6, v7
	v_cvt_pk_bf16_f32 v2, v2, v3
	v_cvt_pk_bf16_f32 v3, v10, v11
	global_store_dwordx4 v[4:5], v[0:3], off
	s_cbranch_vccnz .LBB0_1584
	s_andn2_b64 vcc, exec, s[14:15]
	s_cbranch_vccnz .LBB0_1583
	s_barrier
	s_branch .LBB0_1583

; __device__ __forceinline__ unsigned cvt_pk_bf16(float lo, float hi) { unsigned r; asm volatile("v_cvt_pk_bf16_f32 %0, %1, %2" : "=v"(r) : "v"(lo), "v"(hi)); return r; }
; __device__ __forceinline__ float silu_f(float v) { return v * __builtin_amdgcn_rcpf(1.0f + __builtin_amdgcn_exp2f(v * -1.4426950408889634f)); }
; __device__ __forceinline__ f32x4 silu4(f32x4 v) { return (f32x4){silu_f(v[0]), silu_f(v[1]), silu_f(v[2]), silu_f(v[3])}; }
; __device__ __forceinline__ float sq4(f32x4 v) { return (v[0] * v[0] + v[1] * v[1]) + (v[2] * v[2] + v[3] * v[3]); }
; __device__ __forceinline__ u32x4 pack8(f32x4 a, f32x4 b) { u32x4 w; w.x = cvt_pk_bf16(a[0], a[1]); w.y = cvt_pk_bf16(a[2], a[3]); w.z = cvt_pk_bf16(b[0], b[1]); w.w = cvt_pk_bf16(b[2], b[3]); return w; }
;     __device__ __forceinline__ void operator()(const f32x4 (&acc)[2][2][4][2], const Unit& u, int wr, int wc, int fr, int fq) const {
;     ...
;         for (int ai = 0; ai < 2; ++ai)
; #pragma unroll
;             for (int m = 0; m < 4; ++m) {
;                 const int row = u.pm * BM + ai * HALF + wr * 64 + m * 16 + fr;
;                 const float rstd = rs[ai][m];
;                 const f32x4 a0 = silu4(acc[ai][0][m][0] * rstd) * (acc[ai][1][m][0] * rstd);
;                 const f32x4 a1 = silu4(acc[ai][0][m][1] * rstd) * (acc[ai][1][m][1] * rstd);
;                 *(u32x4*)(ACT + (size_t)row * 2816 + col0) = pack8(a0, a1);
;             }
.Lrsj_3:
	s_mov_b32 s98, 0xbfb8aa3b
	s_mov_b32 s99, 0xbfb8aa3b
	v_mov_b32_e32 v212, 1.0
	v_mov_b32_e32 v213, 1.0
	v_mul_f32_e32 v147, 0xbfb8aa3b, v124
	v_exp_f32_e32 v147, v147
	v_mul_f32_e32 v149, 0xbfb8aa3b, v125
	v_exp_f32_e32 v149, v149
	v_pk_mul_f32 v[126:127], v[126:127], v[176:177] op_sel_hi:[1,0]
	v_add_f32_e32 v147, 1.0, v147
	v_rcp_f32_e32 v178, v147
	v_add_f32_e32 v147, 1.0, v149
	v_mul_f32_e32 v149, 0xbfb8aa3b, v126
	v_exp_f32_e32 v149, v149
	v_mul_f32_e32 v151, 0xbfb8aa3b, v127
	v_exp_f32_e32 v151, v151
	v_rcp_f32_e32 v179, v147
	v_add_f32_e32 v147, 1.0, v149
	v_rcp_f32_e32 v180, v147
	v_add_f32_e32 v147, 1.0, v151
	v_pk_mul_f32 v[120:121], v[120:121], v[176:177] op_sel_hi:[1,0]
	v_rcp_f32_e32 v181, v147
	v_mul_f32_e32 v147, 0xbfb8aa3b, v120
	v_exp_f32_e32 v147, v147
	v_mul_f32_e32 v149, 0xbfb8aa3b, v121
	v_exp_f32_e32 v149, v149
	v_pk_mul_f32 v[122:123], v[122:123], v[176:177] op_sel_hi:[1,0]
	v_add_f32_e32 v147, 1.0, v147
	v_pk_mul_f32 v[124:125], v[124:125], v[178:179]
	v_rcp_f32_e32 v178, v147
	v_add_f32_e32 v147, 1.0, v149
	v_mul_f32_e32 v149, 0xbfb8aa3b, v122
	v_exp_f32_e32 v149, v149
	v_mul_f32_e32 v151, 0xbfb8aa3b, v123
	v_exp_f32_e32 v151, v151
	v_rcp_f32_e32 v179, v147
	v_add_f32_e32 v147, 1.0, v149
	v_pk_mul_f32 v[126:127], v[126:127], v[180:181]
	v_rcp_f32_e32 v180, v147
	v_add_f32_e32 v147, 1.0, v151
	v_rcp_f32_e32 v181, v147
	v_pk_mul_f32 v[116:117], v[116:117], v[176:177] op_sel_hi:[1,0]
	v_pk_mul_f32 v[118:119], v[118:119], v[176:177] op_sel_hi:[1,0]
	v_pk_mul_f32 v[120:121], v[120:121], v[178:179]
	v_pk_mul_f32 v[112:113], v[112:113], v[176:177] op_sel_hi:[1,0]
	v_lshl_or_b32 v182, s48, 7, v161
	v_pk_mul_f32 v[118:119], v[118:119], v[126:127]
	v_pk_mul_f32 v[116:117], v[116:117], v[124:125]
	v_pk_mul_f32 v[122:123], v[122:123], v[180:181]
	v_pk_mul_f32 v[114:115], v[114:115], v[176:177] op_sel_hi:[1,0]
	v_pk_mul_f32 v[112:113], v[112:113], v[120:121]
	v_ashrrev_i32_e32 v183, 31, v182
	v_pk_mul_f32 v[114:115], v[114:115], v[122:123]
	v_cvt_pk_bf16_f32 v116, v116, v117
	v_cvt_pk_bf16_f32 v117, v118, v119
	v_cvt_pk_bf16_f32 v118, v112, v113
	v_mov_b64_e32 v[112:113], s[10:11]
	v_cvt_pk_bf16_f32 v119, v114, v115
	v_mad_i64_i32 v[120:121], s[26:27], v170, s47, v[112:113]
	v_lshlrev_b64 v[114:115], 1, v[182:183]
	v_pk_mul_f32 v[108:109], v[108:109], v[174:175] op_sel_hi:[1,0]
	v_pk_mul_f32 v[110:111], v[110:111], v[174:175] op_sel_hi:[1,0]
	v_pk_mul_f32 v[122:123], v[108:109], s[98:99]
	v_lshl_add_u64 v[120:121], v[120:121], 0, v[114:115]
	v_pk_mul_f32 v[104:105], v[104:105], v[174:175] op_sel_hi:[1,0]
	v_pk_mul_f32 v[106:107], v[106:107], v[174:175] op_sel_hi:[1,0]
	v_exp_f32_e32 v122, v122
	v_exp_f32_e32 v123, v123
	v_pk_mul_f32 v[124:125], v[110:111], s[98:99]
	global_store_dwordx4 v[120:121], v[116:119], off
	v_exp_f32_e32 v124, v124
	v_exp_f32_e32 v125, v125
	v_pk_mul_f32 v[116:117], v[104:105], s[98:99]
	v_pk_mul_f32 v[118:119], v[106:107], s[98:99]
	v_exp_f32_e32 v116, v116
	v_exp_f32_e32 v117, v117
	v_exp_f32_e32 v118, v118
	v_exp_f32_e32 v119, v119
	v_pk_add_f32 v[122:123], v[122:123], v[212:213]
	v_rcp_f32_e32 v122, v122
	v_rcp_f32_e32 v123, v123
	v_pk_add_f32 v[124:125], v[124:125], v[212:213]
	v_pk_add_f32 v[116:117], v[116:117], v[212:213]
	v_pk_add_f32 v[118:119], v[118:119], v[212:213]
	v_rcp_f32_e32 v124, v124
	v_rcp_f32_e32 v125, v125
	v_rcp_f32_e32 v116, v116
	v_rcp_f32_e32 v117, v117
	v_rcp_f32_e32 v118, v118
	v_rcp_f32_e32 v119, v119
	v_pk_mul_f32 v[108:109], v[108:109], v[122:123]
	v_pk_mul_f32 v[100:101], v[100:101], v[174:175] op_sel_hi:[1,0]
	v_pk_mul_f32 v[110:111], v[110:111], v[124:125]
	v_pk_mul_f32 v[102:103], v[102:103], v[174:175] op_sel_hi:[1,0]
	v_pk_mul_f32 v[100:101], v[100:101], v[108:109]
	v_pk_mul_f32 v[104:105], v[104:105], v[116:117]
	v_pk_mul_f32 v[106:107], v[106:107], v[118:119]
	v_pk_mul_f32 v[96:97], v[96:97], v[174:175] op_sel_hi:[1,0]
	v_pk_mul_f32 v[98:99], v[98:99], v[174:175] op_sel_hi:[1,0]
	v_pk_mul_f32 v[102:103], v[102:103], v[110:111]
	v_pk_mul_f32 v[106:107], v[98:99], v[106:107]
	v_pk_mul_f32 v[98:99], v[96:97], v[104:105]
	v_cvt_pk_bf16_f32 v96, v100, v101
	v_mad_i64_i32 v[100:101], s[26:27], v166, s47, v[112:113]
	v_pk_mul_f32 v[92:93], v[92:93], v[172:173] op_sel_hi:[1,0]
	v_cvt_pk_bf16_f32 v97, v102, v103
	v_cvt_pk_bf16_f32 v98, v98, v99
	v_cvt_pk_bf16_f32 v99, v106, v107
	v_pk_mul_f32 v[94:95], v[94:95], v[172:173] op_sel_hi:[1,0]
	v_pk_mul_f32 v[102:103], v[92:93], s[98:99]
	v_lshl_add_u64 v[100:101], v[100:101], 0, v[114:115]
	v_pk_mul_f32 v[88:89], v[88:89], v[172:173] op_sel_hi:[1,0]
	v_pk_mul_f32 v[90:91], v[90:91], v[172:173] op_sel_hi:[1,0]
	v_exp_f32_e32 v102, v102
	v_exp_f32_e32 v103, v103
	v_pk_mul_f32 v[104:105], v[94:95], s[98:99]
	global_store_dwordx4 v[100:101], v[96:99], off
	v_exp_f32_e32 v104, v104
	v_exp_f32_e32 v105, v105
	v_pk_mul_f32 v[96:97], v[88:89], s[98:99]
	v_pk_mul_f32 v[98:99], v[90:91], s[98:99]
	v_exp_f32_e32 v96, v96
	v_exp_f32_e32 v97, v97
	v_exp_f32_e32 v98, v98
	v_exp_f32_e32 v99, v99
	v_pk_add_f32 v[102:103], v[102:103], v[212:213]
	v_rcp_f32_e32 v102, v102
	v_rcp_f32_e32 v103, v103
	v_pk_add_f32 v[104:105], v[104:105], v[212:213]
	v_pk_add_f32 v[96:97], v[96:97], v[212:213]
	v_pk_add_f32 v[98:99], v[98:99], v[212:213]
	v_rcp_f32_e32 v104, v104
	v_rcp_f32_e32 v105, v105
	v_rcp_f32_e32 v96, v96
	v_rcp_f32_e32 v97, v97
	v_rcp_f32_e32 v98, v98
	v_rcp_f32_e32 v99, v99
	v_pk_mul_f32 v[92:93], v[92:93], v[102:103]
	v_pk_mul_f32 v[84:85], v[84:85], v[172:173] op_sel_hi:[1,0]
	v_pk_mul_f32 v[94:95], v[94:95], v[104:105]
	v_pk_mul_f32 v[86:87], v[86:87], v[172:173] op_sel_hi:[1,0]
	v_pk_mul_f32 v[84:85], v[84:85], v[92:93]
; __device__ __forceinline__ unsigned cvt_pk_bf16(float lo, float hi) { unsigned r; asm volatile("v_cvt_pk_bf16_f32 %0, %1, %2" : "=v"(r) : "v"(lo), "v"(hi)); return r; }
; __device__ __forceinline__ float silu_f(float v) { return v * __builtin_amdgcn_rcpf(1.0f + __builtin_amdgcn_exp2f(v * -1.4426950408889634f)); }
; __device__ __forceinline__ f32x4 silu4(f32x4 v) { return (f32x4){silu_f(v[0]), silu_f(v[1]), silu_f(v[2]), silu_f(v[3])}; }
; __device__ __forceinline__ float sq4(f32x4 v) { return (v[0] * v[0] + v[1] * v[1]) + (v[2] * v[2] + v[3] * v[3]); }
; __device__ __forceinline__ u32x4 pack8(f32x4 a, f32x4 b) { u32x4 w; w.x = cvt_pk_bf16(a[0], a[1]); w.y = cvt_pk_bf16(a[2], a[3]); w.z = cvt_pk_bf16(b[0], b[1]); w.w = cvt_pk_bf16(b[2], b[3]); return w; }
;     __device__ __forceinline__ void operator()(const f32x4 (&acc)[2][2][4][2], const Unit& u, int wr, int wc, int fr, int fq) const {
;     ...
;         for (int ai = 0; ai < 2; ++ai)
; #pragma unroll
;             for (int m = 0; m < 4; ++m) {
;                 const int row = u.pm * BM + ai * HALF + wr * 64 + m * 16 + fr;
;                 const float rstd = rs[ai][m];
;                 const f32x4 a0 = silu4(acc[ai][0][m][0] * rstd) * (acc[ai][1][m][0] * rstd);
;                 const f32x4 a1 = silu4(acc[ai][0][m][1] * rstd) * (acc[ai][1][m][1] * rstd);
;                 *(u32x4*)(ACT + (size_t)row * 2816 + col0) = pack8(a0, a1);
;             }
	v_pk_mul_f32 v[88:89], v[88:89], v[96:97]
	v_pk_mul_f32 v[90:91], v[90:91], v[98:99]
	v_pk_mul_f32 v[80:81], v[80:81], v[172:173] op_sel_hi:[1,0]
	v_pk_mul_f32 v[82:83], v[82:83], v[172:173] op_sel_hi:[1,0]
	v_pk_mul_f32 v[86:87], v[86:87], v[94:95]
	v_pk_mul_f32 v[90:91], v[82:83], v[90:91]
	v_pk_mul_f32 v[82:83], v[80:81], v[88:89]
	v_cvt_pk_bf16_f32 v80, v84, v85
	v_mad_i64_i32 v[84:85], s[26:27], v162, s47, v[112:113]
	v_pk_mul_f32 v[76:77], v[76:77], v[168:169] op_sel_hi:[1,0]
	v_cvt_pk_bf16_f32 v81, v86, v87
	v_cvt_pk_bf16_f32 v82, v82, v83
	v_cvt_pk_bf16_f32 v83, v90, v91
	v_pk_mul_f32 v[78:79], v[78:79], v[168:169] op_sel_hi:[1,0]
	v_pk_mul_f32 v[86:87], v[76:77], s[98:99]
	v_lshl_add_u64 v[84:85], v[84:85], 0, v[114:115]
	v_pk_mul_f32 v[72:73], v[72:73], v[168:169] op_sel_hi:[1,0]
	v_pk_mul_f32 v[74:75], v[74:75], v[168:169] op_sel_hi:[1,0]
	v_exp_f32_e32 v86, v86
	v_exp_f32_e32 v87, v87
	v_pk_mul_f32 v[88:89], v[78:79], s[98:99]
	global_store_dwordx4 v[84:85], v[80:83], off
	v_exp_f32_e32 v88, v88
	v_exp_f32_e32 v89, v89
	v_pk_mul_f32 v[80:81], v[72:73], s[98:99]
	v_pk_mul_f32 v[82:83], v[74:75], s[98:99]
	v_exp_f32_e32 v80, v80
	v_exp_f32_e32 v81, v81
	v_exp_f32_e32 v82, v82
	v_exp_f32_e32 v83, v83
	v_pk_add_f32 v[86:87], v[86:87], v[212:213]
	v_rcp_f32_e32 v86, v86
	v_rcp_f32_e32 v87, v87
	v_pk_add_f32 v[88:89], v[88:89], v[212:213]
	v_pk_add_f32 v[80:81], v[80:81], v[212:213]
	v_pk_add_f32 v[82:83], v[82:83], v[212:213]
	v_rcp_f32_e32 v88, v88
	v_rcp_f32_e32 v89, v89
	v_rcp_f32_e32 v80, v80
	v_rcp_f32_e32 v81, v81
	v_rcp_f32_e32 v82, v82
	v_rcp_f32_e32 v83, v83
	v_pk_mul_f32 v[76:77], v[76:77], v[86:87]
	v_pk_mul_f32 v[68:69], v[68:69], v[168:169] op_sel_hi:[1,0]
	v_pk_mul_f32 v[78:79], v[78:79], v[88:89]
	v_pk_mul_f32 v[70:71], v[70:71], v[168:169] op_sel_hi:[1,0]
	v_pk_mul_f32 v[68:69], v[68:69], v[76:77]
	v_pk_mul_f32 v[72:73], v[72:73], v[80:81]
	v_pk_mul_f32 v[74:75], v[74:75], v[82:83]
	v_pk_mul_f32 v[64:65], v[64:65], v[168:169] op_sel_hi:[1,0]
	v_pk_mul_f32 v[66:67], v[66:67], v[168:169] op_sel_hi:[1,0]
	v_pk_mul_f32 v[70:71], v[70:71], v[78:79]
	v_pk_mul_f32 v[74:75], v[66:67], v[74:75]
	v_pk_mul_f32 v[66:67], v[64:65], v[72:73]
	v_cvt_pk_bf16_f32 v64, v68, v69
	v_mad_i64_i32 v[68:69], s[26:27], v158, s47, v[112:113]
	v_pk_mul_f32 v[60:61], v[60:61], v[164:165] op_sel_hi:[1,0]
	v_cvt_pk_bf16_f32 v65, v70, v71
	v_cvt_pk_bf16_f32 v66, v66, v67
	v_cvt_pk_bf16_f32 v67, v74, v75
	v_pk_mul_f32 v[62:63], v[62:63], v[164:165] op_sel_hi:[1,0]
	v_pk_mul_f32 v[70:71], v[60:61], s[98:99]
	v_lshl_add_u64 v[68:69], v[68:69], 0, v[114:115]
	v_pk_mul_f32 v[56:57], v[56:57], v[164:165] op_sel_hi:[1,0]
	v_pk_mul_f32 v[58:59], v[58:59], v[164:165] op_sel_hi:[1,0]
	v_exp_f32_e32 v70, v70
	v_exp_f32_e32 v71, v71
	v_pk_mul_f32 v[72:73], v[62:63], s[98:99]
	global_store_dwordx4 v[68:69], v[64:67], off
	v_exp_f32_e32 v72, v72
	v_exp_f32_e32 v73, v73
	v_pk_mul_f32 v[64:65], v[56:57], s[98:99]
	v_pk_mul_f32 v[66:67], v[58:59], s[98:99]
	v_exp_f32_e32 v64, v64
	v_exp_f32_e32 v65, v65
	v_exp_f32_e32 v66, v66
	v_exp_f32_e32 v67, v67
	v_pk_add_f32 v[70:71], v[70:71], v[212:213]
	v_rcp_f32_e32 v70, v70
	v_rcp_f32_e32 v71, v71
	v_pk_add_f32 v[72:73], v[72:73], v[212:213]
	v_pk_add_f32 v[64:65], v[64:65], v[212:213]
	v_pk_add_f32 v[66:67], v[66:67], v[212:213]
	v_rcp_f32_e32 v72, v72
	v_rcp_f32_e32 v73, v73
	v_rcp_f32_e32 v64, v64
	v_rcp_f32_e32 v65, v65
	v_rcp_f32_e32 v66, v66
	v_rcp_f32_e32 v67, v67
	v_pk_mul_f32 v[60:61], v[60:61], v[70:71]
	v_pk_mul_f32 v[52:53], v[52:53], v[164:165] op_sel_hi:[1,0]
	v_pk_mul_f32 v[62:63], v[62:63], v[72:73]
	v_pk_mul_f32 v[54:55], v[54:55], v[164:165] op_sel_hi:[1,0]
	v_pk_mul_f32 v[52:53], v[52:53], v[60:61]
	v_pk_mul_f32 v[56:57], v[56:57], v[64:65]
	v_pk_mul_f32 v[58:59], v[58:59], v[66:67]
	v_pk_mul_f32 v[48:49], v[48:49], v[164:165] op_sel_hi:[1,0]
	v_pk_mul_f32 v[50:51], v[50:51], v[164:165] op_sel_hi:[1,0]
	v_pk_mul_f32 v[54:55], v[54:55], v[62:63]
	v_pk_mul_f32 v[58:59], v[50:51], v[58:59]
	v_pk_mul_f32 v[50:51], v[48:49], v[56:57]
	v_cvt_pk_bf16_f32 v48, v52, v53
	v_mad_i64_i32 v[52:53], s[26:27], v154, s47, v[112:113]
	v_pk_mul_f32 v[44:45], v[44:45], v[160:161] op_sel_hi:[1,0]
	v_cvt_pk_bf16_f32 v49, v54, v55
	v_cvt_pk_bf16_f32 v50, v50, v51
	v_cvt_pk_bf16_f32 v51, v58, v59
	v_pk_mul_f32 v[46:47], v[46:47], v[160:161] op_sel_hi:[1,0]
	v_pk_mul_f32 v[54:55], v[44:45], s[98:99]
	v_lshl_add_u64 v[52:53], v[52:53], 0, v[114:115]
	v_pk_mul_f32 v[40:41], v[40:41], v[160:161] op_sel_hi:[1,0]
	v_pk_mul_f32 v[42:43], v[42:43], v[160:161] op_sel_hi:[1,0]
	v_exp_f32_e32 v54, v54
	v_exp_f32_e32 v55, v55
	v_pk_mul_f32 v[56:57], v[46:47], s[98:99]
	global_store_dwordx4 v[52:53], v[48:51], off
	v_exp_f32_e32 v56, v56
	v_exp_f32_e32 v57, v57
	v_pk_mul_f32 v[48:49], v[40:41], s[98:99]
	v_pk_mul_f32 v[50:51], v[42:43], s[98:99]
	v_exp_f32_e32 v48, v48
	v_exp_f32_e32 v49, v49
	v_exp_f32_e32 v50, v50
	v_exp_f32_e32 v51, v51
	v_pk_add_f32 v[54:55], v[54:55], v[212:213]
; __device__ __forceinline__ unsigned cvt_pk_bf16(float lo, float hi) { unsigned r; asm volatile("v_cvt_pk_bf16_f32 %0, %1, %2" : "=v"(r) : "v"(lo), "v"(hi)); return r; }
; __device__ __forceinline__ float silu_f(float v) { return v * __builtin_amdgcn_rcpf(1.0f + __builtin_amdgcn_exp2f(v * -1.4426950408889634f)); }
; __device__ __forceinline__ f32x4 silu4(f32x4 v) { return (f32x4){silu_f(v[0]), silu_f(v[1]), silu_f(v[2]), silu_f(v[3])}; }
; __device__ __forceinline__ float sq4(f32x4 v) { return (v[0] * v[0] + v[1] * v[1]) + (v[2] * v[2] + v[3] * v[3]); }
; __device__ __forceinline__ u32x4 pack8(f32x4 a, f32x4 b) { u32x4 w; w.x = cvt_pk_bf16(a[0], a[1]); w.y = cvt_pk_bf16(a[2], a[3]); w.z = cvt_pk_bf16(b[0], b[1]); w.w = cvt_pk_bf16(b[2], b[3]); return w; }
;     __device__ __forceinline__ void operator()(const f32x4 (&acc)[2][2][4][2], const Unit& u, int wr, int wc, int fr, int fq) const {
;     ...
;         for (int ai = 0; ai < 2; ++ai)
; #pragma unroll
;             for (int m = 0; m < 4; ++m) {
;                 const int row = u.pm * BM + ai * HALF + wr * 64 + m * 16 + fr;
;                 const float rstd = rs[ai][m];
;                 const f32x4 a0 = silu4(acc[ai][0][m][0] * rstd) * (acc[ai][1][m][0] * rstd);
;                 const f32x4 a1 = silu4(acc[ai][0][m][1] * rstd) * (acc[ai][1][m][1] * rstd);
;                 *(u32x4*)(ACT + (size_t)row * 2816 + col0) = pack8(a0, a1);
;             }
	v_rcp_f32_e32 v54, v54
	v_rcp_f32_e32 v55, v55
	v_pk_add_f32 v[56:57], v[56:57], v[212:213]
	v_pk_add_f32 v[48:49], v[48:49], v[212:213]
	v_pk_add_f32 v[50:51], v[50:51], v[212:213]
	v_rcp_f32_e32 v56, v56
	v_rcp_f32_e32 v57, v57
	v_rcp_f32_e32 v48, v48
	v_rcp_f32_e32 v49, v49
	v_rcp_f32_e32 v50, v50
	v_rcp_f32_e32 v51, v51
	v_pk_mul_f32 v[44:45], v[44:45], v[54:55]
	v_pk_mul_f32 v[36:37], v[36:37], v[160:161] op_sel_hi:[1,0]
	v_pk_mul_f32 v[46:47], v[46:47], v[56:57]
	v_pk_mul_f32 v[38:39], v[38:39], v[160:161] op_sel_hi:[1,0]
	v_pk_mul_f32 v[36:37], v[36:37], v[44:45]
	v_pk_mul_f32 v[40:41], v[40:41], v[48:49]
	v_pk_mul_f32 v[42:43], v[42:43], v[50:51]
	v_pk_mul_f32 v[32:33], v[32:33], v[160:161] op_sel_hi:[1,0]
	v_pk_mul_f32 v[34:35], v[34:35], v[160:161] op_sel_hi:[1,0]
	v_pk_mul_f32 v[38:39], v[38:39], v[46:47]
	v_pk_mul_f32 v[42:43], v[34:35], v[42:43]
	v_pk_mul_f32 v[34:35], v[32:33], v[40:41]
	v_cvt_pk_bf16_f32 v32, v36, v37
	v_mad_i64_i32 v[36:37], s[26:27], v150, s47, v[112:113]
	v_pk_mul_f32 v[28:29], v[28:29], v[156:157] op_sel_hi:[1,0]
	v_cvt_pk_bf16_f32 v33, v38, v39
	v_cvt_pk_bf16_f32 v34, v34, v35
	v_cvt_pk_bf16_f32 v35, v42, v43
	v_pk_mul_f32 v[30:31], v[30:31], v[156:157] op_sel_hi:[1,0]
	v_pk_mul_f32 v[38:39], v[28:29], s[98:99]
	v_lshl_add_u64 v[36:37], v[36:37], 0, v[114:115]
	v_pk_mul_f32 v[24:25], v[24:25], v[156:157] op_sel_hi:[1,0]
	v_pk_mul_f32 v[26:27], v[26:27], v[156:157] op_sel_hi:[1,0]
	v_exp_f32_e32 v38, v38
	v_exp_f32_e32 v39, v39
	v_pk_mul_f32 v[40:41], v[30:31], s[98:99]
	global_store_dwordx4 v[36:37], v[32:35], off
	v_exp_f32_e32 v40, v40
	v_exp_f32_e32 v41, v41
	v_pk_mul_f32 v[32:33], v[24:25], s[98:99]
	v_pk_mul_f32 v[34:35], v[26:27], s[98:99]
	v_exp_f32_e32 v32, v32
	v_exp_f32_e32 v33, v33
	v_exp_f32_e32 v34, v34
	v_exp_f32_e32 v35, v35
	v_pk_add_f32 v[38:39], v[38:39], v[212:213]
	v_rcp_f32_e32 v38, v38
	v_rcp_f32_e32 v39, v39
	v_pk_add_f32 v[40:41], v[40:41], v[212:213]
	v_pk_add_f32 v[32:33], v[32:33], v[212:213]
	v_pk_add_f32 v[34:35], v[34:35], v[212:213]
	v_rcp_f32_e32 v40, v40
	v_rcp_f32_e32 v41, v41
	v_rcp_f32_e32 v32, v32
	v_rcp_f32_e32 v33, v33
	v_rcp_f32_e32 v34, v34
	v_rcp_f32_e32 v35, v35
	v_pk_mul_f32 v[28:29], v[28:29], v[38:39]
	v_pk_mul_f32 v[20:21], v[20:21], v[156:157] op_sel_hi:[1,0]
	v_pk_mul_f32 v[30:31], v[30:31], v[40:41]
	v_pk_mul_f32 v[22:23], v[22:23], v[156:157] op_sel_hi:[1,0]
	v_pk_mul_f32 v[20:21], v[20:21], v[28:29]
	v_pk_mul_f32 v[24:25], v[24:25], v[32:33]
	v_pk_mul_f32 v[26:27], v[26:27], v[34:35]
	v_pk_mul_f32 v[16:17], v[16:17], v[156:157] op_sel_hi:[1,0]
	v_pk_mul_f32 v[18:19], v[18:19], v[156:157] op_sel_hi:[1,0]
	v_pk_mul_f32 v[22:23], v[22:23], v[30:31]
	v_pk_mul_f32 v[26:27], v[18:19], v[26:27]
	v_pk_mul_f32 v[18:19], v[16:17], v[24:25]
	v_cvt_pk_bf16_f32 v16, v20, v21
	v_mad_i64_i32 v[20:21], s[26:27], v148, s47, v[112:113]
	v_pk_mul_f32 v[12:13], v[12:13], v[152:153] op_sel_hi:[1,0]
	v_cvt_pk_bf16_f32 v17, v22, v23
	v_cvt_pk_bf16_f32 v18, v18, v19
	v_cvt_pk_bf16_f32 v19, v26, v27
	v_lshl_add_u64 v[20:21], v[20:21], 0, v[114:115]
	v_pk_mul_f32 v[22:23], v[12:13], s[98:99]
	v_pk_mul_f32 v[8:9], v[8:9], v[152:153] op_sel_hi:[1,0]
	v_pk_mul_f32 v[10:11], v[10:11], v[152:153] op_sel_hi:[1,0]
	v_exp_f32_e32 v22, v22
	v_exp_f32_e32 v23, v23
	global_store_dwordx4 v[20:21], v[16:19], off
	v_pk_mul_f32 v[14:15], v[14:15], v[152:153] op_sel_hi:[1,0]
	v_add_f32_e32 v22, 1.0, v22
	v_pk_mul_f32 v[16:17], v[8:9], s[98:99]
	v_pk_mul_f32 v[18:19], v[10:11], s[98:99]
	v_exp_f32_e32 v16, v16
	v_exp_f32_e32 v17, v17
	v_exp_f32_e32 v18, v18
	v_exp_f32_e32 v19, v19
	v_pk_mul_f32 v[24:25], v[14:15], s[98:99]
	v_exp_f32_e32 v24, v24
	v_exp_f32_e32 v25, v25
	v_add_f32_e32 v23, 1.0, v23
	v_rcp_f32_e32 v22, v22
	v_rcp_f32_e32 v23, v23
	v_pk_add_f32 v[16:17], v[16:17], v[212:213]
	v_pk_add_f32 v[18:19], v[18:19], v[212:213]
	v_rcp_f32_e32 v16, v16
	v_rcp_f32_e32 v17, v17
	v_rcp_f32_e32 v18, v18
	v_rcp_f32_e32 v19, v19
	v_pk_add_f32 v[24:25], v[24:25], v[212:213]
	v_rcp_f32_e32 v24, v24
	v_rcp_f32_e32 v25, v25
	v_pk_mul_f32 v[12:13], v[12:13], v[22:23]
	v_pk_mul_f32 v[4:5], v[4:5], v[152:153] op_sel_hi:[1,0]
	v_pk_mul_f32 v[8:9], v[8:9], v[16:17]
	v_pk_mul_f32 v[4:5], v[4:5], v[12:13]
	v_pk_mul_f32 v[10:11], v[10:11], v[18:19]
	v_pk_mul_f32 v[0:1], v[0:1], v[152:153] op_sel_hi:[1,0]
	v_pk_mul_f32 v[2:3], v[2:3], v[152:153] op_sel_hi:[1,0]
	v_pk_mul_f32 v[14:15], v[14:15], v[24:25]
	v_pk_mul_f32 v[10:11], v[2:3], v[10:11]
	v_pk_mul_f32 v[2:3], v[0:1], v[8:9]
	v_cvt_pk_bf16_f32 v0, v4, v5
	v_mad_i64_i32 v[4:5], s[26:27], v146, s47, v[112:113]
	v_pk_mul_f32 v[6:7], v[6:7], v[152:153] op_sel_hi:[1,0]
	v_lshl_add_u64 v[4:5], v[4:5], 0, v[114:115]
	v_pk_mul_f32 v[6:7], v[6:7], v[14:15]
	s_nop 0
	v_cvt_pk_bf16_f32 v1, v6, v7
	v_cvt_pk_bf16_f32 v2, v2, v3
	v_cvt_pk_bf16_f32 v3, v10, v11
	global_store_dwordx4 v[4:5], v[0:3], off
	s_cbranch_vccnz .LBB0_2036
	s_andn2_b64 vcc, exec, s[8:9]
	s_cbranch_vccnz .LBB0_2035
	s_barrier
	s_branch .LBB0_2035
